# adds P5 g-chunk preload (no per-step store drain) and P1 rope/W_in epilogue rs1 load hoist
# baseline (speedup 1.0000x reference)
; __device__ __forceinline__ u32x4 pack8f(const f32x4 a, const f32x4 b) { u32x4 w; w.x = cvt_pk_bf16(a[0], a[1]); w.y = cvt_pk_bf16(a[2], a[3]); w.z = cvt_pk_bf16(b[0], b[1]); w.w = cvt_pk_bf16(b[2], b[3]); return w; }
;     __device__ __forceinline__ void operator()(const f32x4 (&acc)[2][2][4][2], const Unit& u, int wr, int wc, int fr, int fq) const {
;         const int sect = u.pn >> 3, hd = u.pn & 7;
;         bf16_t* buf = base + (size_t)sect * ((size_t)QKV_ROWS * 2048);
;         const int j0 = wc * 32 + 8 * fq;
; #pragma unroll
;         for (int ai = 0; ai < 2; ++ai)
; #pragma unroll
;             for (int m = 0; m < 4; ++m) {
;                 const int grow = u.pm * BM + ai * HALF + wr * 64 + m * 16 + fr;
;                 const int pos = NMETA_ + (grow & 4095), srow = (grow >> 12) * TPAD + pos;
;                 const float rr = rs1[grow];
;                 const f32x4 a00 = acc[ai][0][m][0] * rr, a01 = acc[ai][0][m][1] * rr, a10 = acc[ai][1][m][0] * rr, a11 = acc[ai][1][m][1] * rr;
;                 if (sect < 2) {
;                     const int comp = j0 >> 6, i0 = j0 & 63;
;                     const f32x4 c0 = *(const f32x4*)(cosT + pos * 64 + i0), c1 = *(const f32x4*)(cosT + pos * 64 + i0 + 4);
;                     const f32x4 s0 = *(const f32x4*)(sinT + pos * 64 + i0), s1 = *(const f32x4*)(sinT + pos * 64 + i0 + 4);
;                     const f32x4 x1a = a00, x1b = a01, x2a = a10, x2b = a11;
;                     const f32x4 o1a = x1a * c0 - x2a * s0, o1b = x1b * c1 - x2b * s1, o2a = x2a * c0 + x1a * s0, o2b = x2b * c1 + x1b * s1;
;                     const u32x4 w1 = pack8f(o1a, o1b), w2 = pack8f(o2a, o2b);
;                     bf16_t* p = buf + (size_t)srow * 2048 + hd * 256 + comp * 128 + i0;
;                     *(u32x4*)p = w1; *(u32x4*)(p + 64) = w2;
;                 } else {
; #pragma unroll
;                     for (int bj = 0; bj < 2; ++bj) { const u32x4 w = bj ? pack8f(a10, a11) : pack8f(a00, a01);
;                         bf16_t* p = buf + (size_t)srow * 2048 + hd * 256 + bj * HALF + j0;
;                         *(u32x4*)p = w; }
.LBB0_135:
	s_ashr_i32 s35, s44, 3
	s_mul_i32 s3, s35, 0x2100000
	s_mul_hi_i32 s2, s35, 0x2100000
	s_add_u32 s3, s60, s3
	s_addc_u32 s2, s61, s2
	s_cmp_gt_i32 s35, 1
	s_cselect_b64 s[46:47], -1, 0
	s_lshl_b32 s17, s44, 9
	s_and_b32 s17, s17, 0xe00
	s_add_u32 s48, s3, s17
	s_addc_u32 s49, s2, 0
	s_add_u32 s2, s48, s76
	s_addc_u32 s3, s49, 0
	s_lshl_b32 s17, s42, 8
	s_add_i32 s17, s17, s62
	v_or_b32_e32 v154, s17, v158
	v_ashrrev_i32_e32 v155, 31, v154
	v_lshl_add_u64 v[152:153], v[154:155], 2, s[6:7]
	global_load_dword v206, v[152:153], off
	global_load_dword v208, v[152:153], off offset:64
	global_load_dword v210, v[152:153], off offset:128
	global_load_dword v212, v[152:153], off offset:192
	global_load_dword v214, v[152:153], off offset:512
	global_load_dword v216, v[152:153], off offset:576
	global_load_dword v218, v[152:153], off offset:640
	global_load_dword v220, v[152:153], off offset:704
	s_ashr_i32 s44, s17, 12
	s_cmp_lt_i32 s35, 2
	v_and_or_b32 v176, v154, s77, 16
	s_mul_i32 s35, s44, 0x1080
	v_add_u32_e32 v156, s35, v176
	s_mov_b64 s[42:43], -1
	v_lshl_add_u64 v[152:153], s[48:49], 0, v[138:139]
	v_ashrrev_i32_e32 v157, 31, v156
	s_waitcnt vmcnt(0)
	v_mov_b32_e32 v178, v206
	v_pk_mul_f32 v[128:129], v[128:129], v[178:179] op_sel_hi:[1,0]
	v_pk_mul_f32 v[154:155], v[126:127], v[178:179] op_sel_hi:[1,0]
	v_pk_mul_f32 v[124:125], v[124:125], v[178:179] op_sel_hi:[1,0]
	v_pk_mul_f32 v[126:127], v[122:123], v[178:179] op_sel_hi:[1,0]
	v_pk_mul_f32 v[120:121], v[120:121], v[178:179] op_sel_hi:[1,0]
	v_pk_mul_f32 v[122:123], v[118:119], v[178:179] op_sel_hi:[1,0]
	v_pk_mul_f32 v[116:117], v[116:117], v[178:179] op_sel_hi:[1,0]
	v_pk_mul_f32 v[118:119], v[114:115], v[178:179] op_sel_hi:[1,0]
	s_cbranch_scc1 .LBB0_137
	v_lshlrev_b64 v[114:115], 12, v[156:157]
	v_lshl_add_u64 v[114:115], v[152:153], 0, v[114:115]
	v_cvt_pk_bf16_f32 v178, v154, v155
	v_cvt_pk_bf16_f32 v179, v128, v129
	v_cvt_pk_bf16_f32 v180, v126, v127
	v_cvt_pk_bf16_f32 v181, v124, v125
	s_mov_b64 s[42:43], 0
	global_store_dwordx4 v[114:115], v[178:181], off
	s_nop 1
	v_cvt_pk_bf16_f32 v178, v122, v123
	v_cvt_pk_bf16_f32 v179, v120, v121
	v_cvt_pk_bf16_f32 v180, v118, v119
	v_cvt_pk_bf16_f32 v181, v116, v117
	global_store_dwordx4 v[114:115], v[178:181], off offset:256

;     __device__ __forceinline__ void operator()(const f32x4 (&acc)[2][2][4][2], const Unit& u, int wr, int wc, int fr, int fq) const {
;     ...
;                 const int grow = u.pm * BM + ai * HALF + wr * 64 + m * 16 + fr;
;                 const int pos = NMETA_ + (grow & 4095), srow = (grow >> 12) * TPAD + pos;
;                 const float rr = rs1[grow];
;                 const f32x4 a00 = acc[ai][0][m][0] * rr, a01 = acc[ai][0][m][1] * rr, a10 = acc[ai][1][m][0] * rr, a11 = acc[ai][1][m][1] * rr;
.LBB0_139:
	s_nop 0
	v_or_b32_e32 v116, s17, v168
	v_ashrrev_i32_e32 v117, 31, v116
	v_lshl_add_u64 v[116:117], v[116:117], 2, s[6:7]
	s_nop 0
	v_bitop3_b32 v116, s17, v174, v168 bitop3:0xc8
	v_add_u32_e32 v118, 16, v116
	v_cndmask_b32_e64 v117, 0, 1, s[46:47]
	v_add_u32_e32 v116, s35, v118
	s_mov_b64 s[42:43], -1
	v_cmp_ne_u32_e64 s[2:3], 1, v117
	s_andn2_b64 vcc, exec, s[46:47]
	v_ashrrev_i32_e32 v117, 31, v116
	v_mov_b32_e32 v120, v208
	v_pk_mul_f32 v[112:113], v[112:113], v[120:121] op_sel_hi:[1,0]
	v_pk_mul_f32 v[110:111], v[110:111], v[120:121] op_sel_hi:[1,0]
	v_pk_mul_f32 v[108:109], v[108:109], v[120:121] op_sel_hi:[1,0]
	v_pk_mul_f32 v[106:107], v[106:107], v[120:121] op_sel_hi:[1,0]
	v_pk_mul_f32 v[104:105], v[104:105], v[120:121] op_sel_hi:[1,0]
	v_pk_mul_f32 v[102:103], v[102:103], v[120:121] op_sel_hi:[1,0]
	v_pk_mul_f32 v[100:101], v[100:101], v[120:121] op_sel_hi:[1,0]
	v_pk_mul_f32 v[98:99], v[98:99], v[120:121] op_sel_hi:[1,0]
	s_cbranch_vccnz .LBB0_141
	v_lshlrev_b64 v[120:121], 12, v[116:117]
	v_lshl_add_u64 v[124:125], v[152:153], 0, v[120:121]
	v_cvt_pk_bf16_f32 v120, v110, v111
	v_cvt_pk_bf16_f32 v121, v112, v113
	v_cvt_pk_bf16_f32 v122, v106, v107
	v_cvt_pk_bf16_f32 v123, v108, v109
	s_mov_b64 s[42:43], 0
	global_store_dwordx4 v[124:125], v[120:123], off
	s_nop 1
	v_cvt_pk_bf16_f32 v120, v102, v103
	v_cvt_pk_bf16_f32 v121, v104, v105
	v_cvt_pk_bf16_f32 v122, v98, v99
	v_cvt_pk_bf16_f32 v123, v100, v101
	global_store_dwordx4 v[124:125], v[120:123], off offset:256

;     __device__ __forceinline__ void operator()(const f32x4 (&acc)[2][2][4][2], const Unit& u, int wr, int wc, int fr, int fq) const {
;     ...
;                 const int grow = u.pm * BM + ai * HALF + wr * 64 + m * 16 + fr;
;                 const int pos = NMETA_ + (grow & 4095), srow = (grow >> 12) * TPAD + pos;
;                 const float rr = rs1[grow];
;                 const f32x4 a00 = acc[ai][0][m][0] * rr, a01 = acc[ai][0][m][1] * rr, a10 = acc[ai][1][m][0] * rr, a11 = acc[ai][1][m][1] * rr;
.LBB0_143:
	s_nop 0
	v_or_b32_e32 v98, s17, v169
	v_ashrrev_i32_e32 v99, 31, v98
	v_lshl_add_u64 v[100:101], v[98:99], 2, s[6:7]
	s_nop 0
	v_and_or_b32 v100, v98, s78, 16
	v_add_u32_e32 v98, s35, v100
	s_mov_b64 s[42:43], -1
	s_and_b64 vcc, exec, s[2:3]
	v_ashrrev_i32_e32 v99, 31, v98
	v_mov_b32_e32 v102, v210
	v_pk_mul_f32 v[96:97], v[96:97], v[102:103] op_sel_hi:[1,0]
	v_pk_mul_f32 v[94:95], v[94:95], v[102:103] op_sel_hi:[1,0]
	v_pk_mul_f32 v[92:93], v[92:93], v[102:103] op_sel_hi:[1,0]
	v_pk_mul_f32 v[90:91], v[90:91], v[102:103] op_sel_hi:[1,0]
	v_pk_mul_f32 v[88:89], v[88:89], v[102:103] op_sel_hi:[1,0]
	v_pk_mul_f32 v[86:87], v[86:87], v[102:103] op_sel_hi:[1,0]
	v_pk_mul_f32 v[84:85], v[84:85], v[102:103] op_sel_hi:[1,0]
	v_pk_mul_f32 v[82:83], v[82:83], v[102:103] op_sel_hi:[1,0]
	s_cbranch_vccnz .LBB0_145
	v_lshlrev_b64 v[102:103], 12, v[98:99]
	v_lshl_add_u64 v[106:107], v[152:153], 0, v[102:103]
	v_cvt_pk_bf16_f32 v102, v94, v95
	v_cvt_pk_bf16_f32 v103, v96, v97
	v_cvt_pk_bf16_f32 v104, v90, v91
	v_cvt_pk_bf16_f32 v105, v92, v93
	s_mov_b64 s[42:43], 0
	global_store_dwordx4 v[106:107], v[102:105], off
	s_nop 1
	v_cvt_pk_bf16_f32 v102, v86, v87
	v_cvt_pk_bf16_f32 v103, v88, v89
	v_cvt_pk_bf16_f32 v104, v82, v83
	v_cvt_pk_bf16_f32 v105, v84, v85
	global_store_dwordx4 v[106:107], v[102:105], off offset:256

;     __device__ __forceinline__ void operator()(const f32x4 (&acc)[2][2][4][2], const Unit& u, int wr, int wc, int fr, int fq) const {
;     ...
;                 const int grow = u.pm * BM + ai * HALF + wr * 64 + m * 16 + fr;
;                 const int pos = NMETA_ + (grow & 4095), srow = (grow >> 12) * TPAD + pos;
;                 const float rr = rs1[grow];
;                 const f32x4 a00 = acc[ai][0][m][0] * rr, a01 = acc[ai][0][m][1] * rr, a10 = acc[ai][1][m][0] * rr, a11 = acc[ai][1][m][1] * rr;
.LBB0_147:
	s_nop 0
	v_or_b32_e32 v82, s17, v170
	v_ashrrev_i32_e32 v83, 31, v82
	v_lshl_add_u64 v[82:83], v[82:83], 2, s[6:7]
	s_nop 0
	v_bitop3_b32 v82, s17, v175, v170 bitop3:0xc8
	v_add_u32_e32 v84, 16, v82
	v_add_u32_e32 v82, s35, v84
	s_mov_b64 s[42:43], -1
	s_and_b64 vcc, exec, s[2:3]
	v_ashrrev_i32_e32 v83, 31, v82
	v_mov_b32_e32 v86, v212
	v_pk_mul_f32 v[80:81], v[80:81], v[86:87] op_sel_hi:[1,0]
	v_pk_mul_f32 v[78:79], v[78:79], v[86:87] op_sel_hi:[1,0]
	v_pk_mul_f32 v[76:77], v[76:77], v[86:87] op_sel_hi:[1,0]
	v_pk_mul_f32 v[74:75], v[74:75], v[86:87] op_sel_hi:[1,0]
	v_pk_mul_f32 v[72:73], v[72:73], v[86:87] op_sel_hi:[1,0]
	v_pk_mul_f32 v[70:71], v[70:71], v[86:87] op_sel_hi:[1,0]
	v_pk_mul_f32 v[68:69], v[68:69], v[86:87] op_sel_hi:[1,0]
	v_pk_mul_f32 v[66:67], v[66:67], v[86:87] op_sel_hi:[1,0]
	s_cbranch_vccnz .LBB0_149
	v_lshlrev_b64 v[86:87], 12, v[82:83]
	v_lshl_add_u64 v[90:91], v[152:153], 0, v[86:87]
	v_cvt_pk_bf16_f32 v86, v78, v79
	v_cvt_pk_bf16_f32 v87, v80, v81
	v_cvt_pk_bf16_f32 v88, v74, v75
	v_cvt_pk_bf16_f32 v89, v76, v77
	s_mov_b64 s[42:43], 0
	global_store_dwordx4 v[90:91], v[86:89], off
	s_nop 1
	v_cvt_pk_bf16_f32 v86, v70, v71
	v_cvt_pk_bf16_f32 v87, v72, v73
	v_cvt_pk_bf16_f32 v88, v66, v67
	v_cvt_pk_bf16_f32 v89, v68, v69
	global_store_dwordx4 v[90:91], v[86:89], off offset:256

;     __device__ __forceinline__ void operator()(const f32x4 (&acc)[2][2][4][2], const Unit& u, int wr, int wc, int fr, int fq) const {
;     ...
;                 const int grow = u.pm * BM + ai * HALF + wr * 64 + m * 16 + fr;
;                 const int pos = NMETA_ + (grow & 4095), srow = (grow >> 12) * TPAD + pos;
;                 const float rr = rs1[grow];
;                 const f32x4 a00 = acc[ai][0][m][0] * rr, a01 = acc[ai][0][m][1] * rr, a10 = acc[ai][1][m][0] * rr, a11 = acc[ai][1][m][1] * rr;
.LBB0_151:
	s_addk_i32 s17, 0x80
	v_or_b32_e32 v66, s17, v158
	v_ashrrev_i32_e32 v67, 31, v66
	v_lshl_add_u64 v[68:69], v[66:67], 2, s[6:7]
	s_nop 0
	s_ashr_i32 s35, s17, 12
	v_and_or_b32 v68, v66, s77, 16
	s_mulk_i32 s35, 0x1080
	v_add_u32_e32 v66, s35, v68
	s_mov_b64 s[42:43], -1
	s_and_b64 vcc, exec, s[2:3]
	v_ashrrev_i32_e32 v67, 31, v66
	v_mov_b32_e32 v70, v214
	v_pk_mul_f32 v[64:65], v[64:65], v[70:71] op_sel_hi:[1,0]
	v_pk_mul_f32 v[62:63], v[62:63], v[70:71] op_sel_hi:[1,0]
	v_pk_mul_f32 v[60:61], v[60:61], v[70:71] op_sel_hi:[1,0]
	v_pk_mul_f32 v[58:59], v[58:59], v[70:71] op_sel_hi:[1,0]
	v_pk_mul_f32 v[56:57], v[56:57], v[70:71] op_sel_hi:[1,0]
	v_pk_mul_f32 v[54:55], v[54:55], v[70:71] op_sel_hi:[1,0]
	v_pk_mul_f32 v[52:53], v[52:53], v[70:71] op_sel_hi:[1,0]
	v_pk_mul_f32 v[50:51], v[50:51], v[70:71] op_sel_hi:[1,0]
	s_cbranch_vccnz .LBB0_153
	v_lshlrev_b64 v[70:71], 12, v[66:67]
	v_lshl_add_u64 v[74:75], v[152:153], 0, v[70:71]
	v_cvt_pk_bf16_f32 v70, v62, v63
	v_cvt_pk_bf16_f32 v71, v64, v65
	v_cvt_pk_bf16_f32 v72, v58, v59
	v_cvt_pk_bf16_f32 v73, v60, v61
	s_mov_b64 s[42:43], 0
	global_store_dwordx4 v[74:75], v[70:73], off
	s_nop 1
	v_cvt_pk_bf16_f32 v70, v54, v55
	v_cvt_pk_bf16_f32 v71, v56, v57
	v_cvt_pk_bf16_f32 v72, v50, v51
	v_cvt_pk_bf16_f32 v73, v52, v53
	global_store_dwordx4 v[74:75], v[70:73], off offset:256

;     __device__ __forceinline__ void operator()(const f32x4 (&acc)[2][2][4][2], const Unit& u, int wr, int wc, int fr, int fq) const {
;     ...
;                 const int grow = u.pm * BM + ai * HALF + wr * 64 + m * 16 + fr;
;                 const int pos = NMETA_ + (grow & 4095), srow = (grow >> 12) * TPAD + pos;
;                 const float rr = rs1[grow];
;                 const f32x4 a00 = acc[ai][0][m][0] * rr, a01 = acc[ai][0][m][1] * rr, a10 = acc[ai][1][m][0] * rr, a11 = acc[ai][1][m][1] * rr;
.LBB0_155:
	s_nop 0
	v_or_b32_e32 v50, s17, v168
	v_ashrrev_i32_e32 v51, 31, v50
	v_lshl_add_u64 v[50:51], v[50:51], 2, s[6:7]
	s_nop 0
	v_bitop3_b32 v50, s17, v174, v168 bitop3:0xc8
	v_add_u32_e32 v52, 16, v50
	v_add_u32_e32 v50, s35, v52
	s_mov_b64 s[42:43], -1
	s_and_b64 vcc, exec, s[2:3]
	v_ashrrev_i32_e32 v51, 31, v50
	v_mov_b32_e32 v54, v216
	v_pk_mul_f32 v[48:49], v[48:49], v[54:55] op_sel_hi:[1,0]
	v_pk_mul_f32 v[46:47], v[46:47], v[54:55] op_sel_hi:[1,0]
	v_pk_mul_f32 v[44:45], v[44:45], v[54:55] op_sel_hi:[1,0]
	v_pk_mul_f32 v[42:43], v[42:43], v[54:55] op_sel_hi:[1,0]
	v_pk_mul_f32 v[40:41], v[40:41], v[54:55] op_sel_hi:[1,0]
	v_pk_mul_f32 v[38:39], v[38:39], v[54:55] op_sel_hi:[1,0]
	v_pk_mul_f32 v[36:37], v[36:37], v[54:55] op_sel_hi:[1,0]
	v_pk_mul_f32 v[34:35], v[34:35], v[54:55] op_sel_hi:[1,0]
	s_cbranch_vccnz .LBB0_157
	v_lshlrev_b64 v[54:55], 12, v[50:51]
	v_lshl_add_u64 v[58:59], v[152:153], 0, v[54:55]
	v_cvt_pk_bf16_f32 v54, v46, v47
	v_cvt_pk_bf16_f32 v55, v48, v49
	v_cvt_pk_bf16_f32 v56, v42, v43
	v_cvt_pk_bf16_f32 v57, v44, v45
	s_mov_b64 s[42:43], 0
	global_store_dwordx4 v[58:59], v[54:57], off
	s_nop 1
	v_cvt_pk_bf16_f32 v54, v38, v39
	v_cvt_pk_bf16_f32 v55, v40, v41
	v_cvt_pk_bf16_f32 v56, v34, v35
	v_cvt_pk_bf16_f32 v57, v36, v37
	global_store_dwordx4 v[58:59], v[54:57], off offset:256

;     __device__ __forceinline__ void operator()(const f32x4 (&acc)[2][2][4][2], const Unit& u, int wr, int wc, int fr, int fq) const {
;     ...
;                 const int grow = u.pm * BM + ai * HALF + wr * 64 + m * 16 + fr;
;                 const int pos = NMETA_ + (grow & 4095), srow = (grow >> 12) * TPAD + pos;
;                 const float rr = rs1[grow];
;                 const f32x4 a00 = acc[ai][0][m][0] * rr, a01 = acc[ai][0][m][1] * rr, a10 = acc[ai][1][m][0] * rr, a11 = acc[ai][1][m][1] * rr;
.LBB0_159:
	s_nop 0
	v_or_b32_e32 v34, s17, v169
	v_ashrrev_i32_e32 v35, 31, v34
	v_lshl_add_u64 v[36:37], v[34:35], 2, s[6:7]
	s_nop 0
	v_and_or_b32 v36, v34, s78, 16
	v_add_u32_e32 v34, s35, v36
	s_mov_b64 s[42:43], -1
	s_and_b64 vcc, exec, s[2:3]
	v_ashrrev_i32_e32 v35, 31, v34
	v_mov_b32_e32 v38, v218
	v_pk_mul_f32 v[32:33], v[32:33], v[38:39] op_sel_hi:[1,0]
	v_pk_mul_f32 v[30:31], v[30:31], v[38:39] op_sel_hi:[1,0]
	v_pk_mul_f32 v[28:29], v[28:29], v[38:39] op_sel_hi:[1,0]
	v_pk_mul_f32 v[26:27], v[26:27], v[38:39] op_sel_hi:[1,0]
	v_pk_mul_f32 v[24:25], v[24:25], v[38:39] op_sel_hi:[1,0]
	v_pk_mul_f32 v[22:23], v[22:23], v[38:39] op_sel_hi:[1,0]
	v_pk_mul_f32 v[20:21], v[20:21], v[38:39] op_sel_hi:[1,0]
	v_pk_mul_f32 v[18:19], v[18:19], v[38:39] op_sel_hi:[1,0]
	s_cbranch_vccnz .LBB0_161
	v_lshlrev_b64 v[38:39], 12, v[34:35]
	v_lshl_add_u64 v[42:43], v[152:153], 0, v[38:39]
	v_cvt_pk_bf16_f32 v38, v30, v31
	v_cvt_pk_bf16_f32 v39, v32, v33
	v_cvt_pk_bf16_f32 v40, v26, v27
	v_cvt_pk_bf16_f32 v41, v28, v29
	s_mov_b64 s[42:43], 0
	global_store_dwordx4 v[42:43], v[38:41], off
	s_nop 1
	v_cvt_pk_bf16_f32 v38, v22, v23
	v_cvt_pk_bf16_f32 v39, v24, v25
	v_cvt_pk_bf16_f32 v40, v18, v19
	v_cvt_pk_bf16_f32 v41, v20, v21
	global_store_dwordx4 v[42:43], v[38:41], off offset:256

;     __device__ __forceinline__ void operator()(const f32x4 (&acc)[2][2][4][2], const Unit& u, int wr, int wc, int fr, int fq) const {
;     ...
;                 const int grow = u.pm * BM + ai * HALF + wr * 64 + m * 16 + fr;
;                 const int pos = NMETA_ + (grow & 4095), srow = (grow >> 12) * TPAD + pos;
;                 const float rr = rs1[grow];
;                 const f32x4 a00 = acc[ai][0][m][0] * rr, a01 = acc[ai][0][m][1] * rr, a10 = acc[ai][1][m][0] * rr, a11 = acc[ai][1][m][1] * rr;
.LBB0_163:
	s_nop 0
	v_or_b32_e32 v18, s17, v170
	v_ashrrev_i32_e32 v19, 31, v18
	v_lshl_add_u64 v[18:19], v[18:19], 2, s[6:7]
	s_nop 0
	v_bitop3_b32 v18, s17, v175, v170 bitop3:0xc8
	v_add_u32_e32 v20, 16, v18
	v_add_u32_e32 v18, s35, v20
	s_mov_b64 s[42:43], -1
	s_and_b64 vcc, exec, s[2:3]
	v_ashrrev_i32_e32 v19, 31, v18
	v_mov_b32_e32 v22, v220
	v_pk_mul_f32 v[16:17], v[16:17], v[22:23] op_sel_hi:[1,0]
	v_pk_mul_f32 v[14:15], v[14:15], v[22:23] op_sel_hi:[1,0]
	v_pk_mul_f32 v[12:13], v[12:13], v[22:23] op_sel_hi:[1,0]
	v_pk_mul_f32 v[10:11], v[10:11], v[22:23] op_sel_hi:[1,0]
	v_pk_mul_f32 v[8:9], v[8:9], v[22:23] op_sel_hi:[1,0]
	v_pk_mul_f32 v[6:7], v[6:7], v[22:23] op_sel_hi:[1,0]
	v_pk_mul_f32 v[4:5], v[4:5], v[22:23] op_sel_hi:[1,0]
	v_pk_mul_f32 v[2:3], v[2:3], v[22:23] op_sel_hi:[1,0]
	s_cbranch_vccz .LBB0_166
	s_andn2_b64 vcc, exec, s[42:43]
	s_cbranch_vccz .LBB0_167

; __device__ __forceinline__ u32x4 pack8f(const f32x4 a, const f32x4 b) { u32x4 w; w.x = cvt_pk_bf16(a[0], a[1]); w.y = cvt_pk_bf16(a[2], a[3]); w.z = cvt_pk_bf16(b[0], b[1]); w.w = cvt_pk_bf16(b[2], b[3]); return w; }
;     __device__ __forceinline__ void operator()(const f32x4 (&acc)[2][2][4][2], const Unit& u, int wr, int wc, int fr, int fq) const {
;         const int sect = u.pn >> 3, hd = u.pn & 7;
;         bf16_t* buf = base + (size_t)sect * ((size_t)QKV_ROWS * 2048);
;         const int j0 = wc * 32 + 8 * fq;
; #pragma unroll
;         for (int ai = 0; ai < 2; ++ai)
; #pragma unroll
;             for (int m = 0; m < 4; ++m) {
;                 const int grow = u.pm * BM + ai * HALF + wr * 64 + m * 16 + fr;
;                 const int pos = NMETA_ + (grow & 4095), srow = (grow >> 12) * TPAD + pos;
;                 const float rr = rs1[grow];
;                 const f32x4 a00 = acc[ai][0][m][0] * rr, a01 = acc[ai][0][m][1] * rr, a10 = acc[ai][1][m][0] * rr, a11 = acc[ai][1][m][1] * rr;
;                 if (sect < 2) {
;                     const int comp = j0 >> 6, i0 = j0 & 63;
;                     const f32x4 c0 = *(const f32x4*)(cosT + pos * 64 + i0), c1 = *(const f32x4*)(cosT + pos * 64 + i0 + 4);
;                     const f32x4 s0 = *(const f32x4*)(sinT + pos * 64 + i0), s1 = *(const f32x4*)(sinT + pos * 64 + i0 + 4);
;                     const f32x4 x1a = a00, x1b = a01, x2a = a10, x2b = a11;
;                     const f32x4 o1a = x1a * c0 - x2a * s0, o1b = x1b * c1 - x2b * s1, o2a = x2a * c0 + x1a * s0, o2b = x2b * c1 + x1b * s1;
;                     const u32x4 w1 = pack8f(o1a, o1b), w2 = pack8f(o2a, o2b);
;                     bf16_t* p = buf + (size_t)srow * 2048 + hd * 256 + comp * 128 + i0;
;                     *(u32x4*)p = w1; *(u32x4*)(p + 64) = w2;
;                 } else {
; #pragma unroll
;                     for (int bj = 0; bj < 2; ++bj) { const u32x4 w = bj ? pack8f(a10, a11) : pack8f(a00, a01);
;                         bf16_t* p = buf + (size_t)srow * 2048 + hd * 256 + bj * HALF + j0;
;                         *(u32x4*)p = w; }
.LBB0_220:
	s_ashr_i32 s35, s42, 3
	s_mul_i32 s17, s35, 0x2100000
	s_mul_hi_i32 s3, s35, 0x2100000
	s_add_u32 s17, s61, s17
	s_addc_u32 s3, s62, s3
	s_cmp_gt_i32 s35, 1
	s_cselect_b64 s[44:45], -1, 0
	s_lshl_b32 s42, s42, 9
	s_and_b32 s42, s42, 0xe00
	s_add_u32 s46, s17, s42
	s_addc_u32 s47, s3, 0
	s_add_u32 s42, s46, s75
	s_addc_u32 s43, s47, 0
	s_lshl_b32 s17, s2, 8
	s_add_i32 s17, s17, s63
	v_or_b32_e32 v154, s17, v158
	v_ashrrev_i32_e32 v155, 31, v154
	v_lshl_add_u64 v[152:153], v[154:155], 2, s[6:7]
	global_load_dword v206, v[152:153], off
	global_load_dword v208, v[152:153], off offset:64
	global_load_dword v210, v[152:153], off offset:128
	global_load_dword v212, v[152:153], off offset:192
	global_load_dword v214, v[152:153], off offset:512
	global_load_dword v216, v[152:153], off offset:576
	global_load_dword v218, v[152:153], off offset:640
	global_load_dword v220, v[152:153], off offset:704
	v_lshl_add_u64 v[152:153], s[46:47], 0, v[138:139]
	s_ashr_i32 s46, s17, 12
	s_cmp_lt_i32 s35, 2
	v_and_or_b32 v168, v154, s76, 16
	s_mul_i32 s35, s46, 0x1080
	v_add_u32_e32 v156, s35, v168
	s_mov_b64 s[2:3], -1
	v_ashrrev_i32_e32 v157, 31, v156
	s_waitcnt vmcnt(0)
	v_mov_b32_e32 v170, v206
	v_pk_mul_f32 v[128:129], v[128:129], v[170:171] op_sel_hi:[1,0]
	v_pk_mul_f32 v[154:155], v[126:127], v[170:171] op_sel_hi:[1,0]
	v_pk_mul_f32 v[124:125], v[124:125], v[170:171] op_sel_hi:[1,0]
	v_pk_mul_f32 v[126:127], v[122:123], v[170:171] op_sel_hi:[1,0]
	v_pk_mul_f32 v[120:121], v[120:121], v[170:171] op_sel_hi:[1,0]
	v_pk_mul_f32 v[122:123], v[118:119], v[170:171] op_sel_hi:[1,0]
	v_pk_mul_f32 v[116:117], v[116:117], v[170:171] op_sel_hi:[1,0]
	v_pk_mul_f32 v[118:119], v[114:115], v[170:171] op_sel_hi:[1,0]
	s_cbranch_scc1 .LBB0_222
	v_lshlrev_b64 v[114:115], 12, v[156:157]
	v_lshl_add_u64 v[114:115], v[152:153], 0, v[114:115]
	v_cvt_pk_bf16_f32 v170, v154, v155
	v_cvt_pk_bf16_f32 v171, v128, v129
	v_cvt_pk_bf16_f32 v172, v126, v127
	v_cvt_pk_bf16_f32 v173, v124, v125
	s_mov_b64 s[2:3], 0
	global_store_dwordx4 v[114:115], v[170:173], off
	s_nop 1
	v_cvt_pk_bf16_f32 v170, v122, v123
	v_cvt_pk_bf16_f32 v171, v120, v121
	v_cvt_pk_bf16_f32 v172, v118, v119
	v_cvt_pk_bf16_f32 v173, v116, v117
	global_store_dwordx4 v[114:115], v[170:173], off offset:256

;     __device__ __forceinline__ void operator()(const f32x4 (&acc)[2][2][4][2], const Unit& u, int wr, int wc, int fr, int fq) const {
;     ...
;                 const int grow = u.pm * BM + ai * HALF + wr * 64 + m * 16 + fr;
;                 const int pos = NMETA_ + (grow & 4095), srow = (grow >> 12) * TPAD + pos;
;                 const float rr = rs1[grow];
;                 const f32x4 a00 = acc[ai][0][m][0] * rr, a01 = acc[ai][0][m][1] * rr, a10 = acc[ai][1][m][0] * rr, a11 = acc[ai][1][m][1] * rr;
.LBB0_224:
	s_nop 0
	v_or_b32_e32 v116, s17, v163
	v_ashrrev_i32_e32 v117, 31, v116
	v_lshl_add_u64 v[116:117], v[116:117], 2, s[6:7]
	s_nop 0
	v_bitop3_b32 v116, s17, v162, v163 bitop3:0xc8
	v_add_u32_e32 v118, 16, v116
	v_cndmask_b32_e64 v117, 0, 1, s[44:45]
	v_add_u32_e32 v116, s35, v118
	s_mov_b64 s[42:43], -1
	v_cmp_ne_u32_e64 s[2:3], 1, v117
	s_andn2_b64 vcc, exec, s[44:45]
	v_ashrrev_i32_e32 v117, 31, v116
	v_mov_b32_e32 v120, v208
	v_pk_mul_f32 v[112:113], v[112:113], v[120:121] op_sel_hi:[1,0]
	v_pk_mul_f32 v[110:111], v[110:111], v[120:121] op_sel_hi:[1,0]
	v_pk_mul_f32 v[108:109], v[108:109], v[120:121] op_sel_hi:[1,0]
	v_pk_mul_f32 v[106:107], v[106:107], v[120:121] op_sel_hi:[1,0]
	v_pk_mul_f32 v[104:105], v[104:105], v[120:121] op_sel_hi:[1,0]
	v_pk_mul_f32 v[102:103], v[102:103], v[120:121] op_sel_hi:[1,0]
	v_pk_mul_f32 v[100:101], v[100:101], v[120:121] op_sel_hi:[1,0]
	v_pk_mul_f32 v[98:99], v[98:99], v[120:121] op_sel_hi:[1,0]
	s_cbranch_vccnz .LBB0_226
	v_lshlrev_b64 v[120:121], 12, v[116:117]
	v_lshl_add_u64 v[124:125], v[152:153], 0, v[120:121]
	v_cvt_pk_bf16_f32 v120, v110, v111
	v_cvt_pk_bf16_f32 v121, v112, v113
	v_cvt_pk_bf16_f32 v122, v106, v107
	v_cvt_pk_bf16_f32 v123, v108, v109
	s_mov_b64 s[42:43], 0
	global_store_dwordx4 v[124:125], v[120:123], off
	s_nop 1
	v_cvt_pk_bf16_f32 v120, v102, v103
	v_cvt_pk_bf16_f32 v121, v104, v105
	v_cvt_pk_bf16_f32 v122, v98, v99
	v_cvt_pk_bf16_f32 v123, v100, v101
	global_store_dwordx4 v[124:125], v[120:123], off offset:256

;     __device__ __forceinline__ void operator()(const f32x4 (&acc)[2][2][4][2], const Unit& u, int wr, int wc, int fr, int fq) const {
;     ...
;                 const int grow = u.pm * BM + ai * HALF + wr * 64 + m * 16 + fr;
;                 const int pos = NMETA_ + (grow & 4095), srow = (grow >> 12) * TPAD + pos;
;                 const float rr = rs1[grow];
;                 const f32x4 a00 = acc[ai][0][m][0] * rr, a01 = acc[ai][0][m][1] * rr, a10 = acc[ai][1][m][0] * rr, a11 = acc[ai][1][m][1] * rr;
.LBB0_228:
	s_nop 0
	v_or_b32_e32 v98, s17, v165
	v_ashrrev_i32_e32 v99, 31, v98
	v_lshl_add_u64 v[100:101], v[98:99], 2, s[6:7]
	s_nop 0
	v_and_or_b32 v100, v98, s77, 16
	v_add_u32_e32 v98, s35, v100
	s_mov_b64 s[42:43], -1
	s_and_b64 vcc, exec, s[2:3]
	v_ashrrev_i32_e32 v99, 31, v98
	v_mov_b32_e32 v102, v210
	v_pk_mul_f32 v[96:97], v[96:97], v[102:103] op_sel_hi:[1,0]
	v_pk_mul_f32 v[94:95], v[94:95], v[102:103] op_sel_hi:[1,0]
	v_pk_mul_f32 v[92:93], v[92:93], v[102:103] op_sel_hi:[1,0]
	v_pk_mul_f32 v[90:91], v[90:91], v[102:103] op_sel_hi:[1,0]
	v_pk_mul_f32 v[88:89], v[88:89], v[102:103] op_sel_hi:[1,0]
	v_pk_mul_f32 v[86:87], v[86:87], v[102:103] op_sel_hi:[1,0]
	v_pk_mul_f32 v[84:85], v[84:85], v[102:103] op_sel_hi:[1,0]
	v_pk_mul_f32 v[82:83], v[82:83], v[102:103] op_sel_hi:[1,0]
	s_cbranch_vccnz .LBB0_230
	v_lshlrev_b64 v[102:103], 12, v[98:99]
	v_lshl_add_u64 v[106:107], v[152:153], 0, v[102:103]
	v_cvt_pk_bf16_f32 v102, v94, v95
	v_cvt_pk_bf16_f32 v103, v96, v97
	v_cvt_pk_bf16_f32 v104, v90, v91
	v_cvt_pk_bf16_f32 v105, v92, v93
	s_mov_b64 s[42:43], 0
	global_store_dwordx4 v[106:107], v[102:105], off
	s_nop 1
	v_cvt_pk_bf16_f32 v102, v86, v87
	v_cvt_pk_bf16_f32 v103, v88, v89
	v_cvt_pk_bf16_f32 v104, v82, v83
	v_cvt_pk_bf16_f32 v105, v84, v85
	global_store_dwordx4 v[106:107], v[102:105], off offset:256

;     __device__ __forceinline__ void operator()(const f32x4 (&acc)[2][2][4][2], const Unit& u, int wr, int wc, int fr, int fq) const {
;     ...
;                 const int grow = u.pm * BM + ai * HALF + wr * 64 + m * 16 + fr;
;                 const int pos = NMETA_ + (grow & 4095), srow = (grow >> 12) * TPAD + pos;
;                 const float rr = rs1[grow];
;                 const f32x4 a00 = acc[ai][0][m][0] * rr, a01 = acc[ai][0][m][1] * rr, a10 = acc[ai][1][m][0] * rr, a11 = acc[ai][1][m][1] * rr;
.LBB0_232:
	s_nop 0
	v_or_b32_e32 v82, s17, v166
	v_ashrrev_i32_e32 v83, 31, v82
	v_lshl_add_u64 v[82:83], v[82:83], 2, s[6:7]
	s_nop 0
	v_bitop3_b32 v82, s17, v167, v166 bitop3:0xc8
	v_add_u32_e32 v84, 16, v82
	v_add_u32_e32 v82, s35, v84
	s_mov_b64 s[42:43], -1
	s_and_b64 vcc, exec, s[2:3]
	v_ashrrev_i32_e32 v83, 31, v82
	v_mov_b32_e32 v86, v212
	v_pk_mul_f32 v[80:81], v[80:81], v[86:87] op_sel_hi:[1,0]
	v_pk_mul_f32 v[78:79], v[78:79], v[86:87] op_sel_hi:[1,0]
	v_pk_mul_f32 v[76:77], v[76:77], v[86:87] op_sel_hi:[1,0]
	v_pk_mul_f32 v[74:75], v[74:75], v[86:87] op_sel_hi:[1,0]
	v_pk_mul_f32 v[72:73], v[72:73], v[86:87] op_sel_hi:[1,0]
	v_pk_mul_f32 v[70:71], v[70:71], v[86:87] op_sel_hi:[1,0]
	v_pk_mul_f32 v[68:69], v[68:69], v[86:87] op_sel_hi:[1,0]
	v_pk_mul_f32 v[66:67], v[66:67], v[86:87] op_sel_hi:[1,0]
	s_cbranch_vccnz .LBB0_234
	v_lshlrev_b64 v[86:87], 12, v[82:83]
	v_lshl_add_u64 v[90:91], v[152:153], 0, v[86:87]
	v_cvt_pk_bf16_f32 v86, v78, v79
	v_cvt_pk_bf16_f32 v87, v80, v81
	v_cvt_pk_bf16_f32 v88, v74, v75
	v_cvt_pk_bf16_f32 v89, v76, v77
	s_mov_b64 s[42:43], 0
	global_store_dwordx4 v[90:91], v[86:89], off
	s_nop 1
	v_cvt_pk_bf16_f32 v86, v70, v71
	v_cvt_pk_bf16_f32 v87, v72, v73
	v_cvt_pk_bf16_f32 v88, v66, v67
	v_cvt_pk_bf16_f32 v89, v68, v69
	global_store_dwordx4 v[90:91], v[86:89], off offset:256

;     __device__ __forceinline__ void operator()(const f32x4 (&acc)[2][2][4][2], const Unit& u, int wr, int wc, int fr, int fq) const {
;     ...
;                 const int grow = u.pm * BM + ai * HALF + wr * 64 + m * 16 + fr;
;                 const int pos = NMETA_ + (grow & 4095), srow = (grow >> 12) * TPAD + pos;
;                 const float rr = rs1[grow];
;                 const f32x4 a00 = acc[ai][0][m][0] * rr, a01 = acc[ai][0][m][1] * rr, a10 = acc[ai][1][m][0] * rr, a11 = acc[ai][1][m][1] * rr;
.LBB0_236:
	s_addk_i32 s17, 0x80
	v_or_b32_e32 v66, s17, v158
	v_ashrrev_i32_e32 v67, 31, v66
	v_lshl_add_u64 v[68:69], v[66:67], 2, s[6:7]
	s_nop 0
	s_ashr_i32 s35, s17, 12
	v_and_or_b32 v68, v66, s76, 16
	s_mulk_i32 s35, 0x1080
	v_add_u32_e32 v66, s35, v68
	s_mov_b64 s[42:43], -1
	s_and_b64 vcc, exec, s[2:3]
	v_ashrrev_i32_e32 v67, 31, v66
	v_mov_b32_e32 v70, v214
	v_pk_mul_f32 v[64:65], v[64:65], v[70:71] op_sel_hi:[1,0]
	v_pk_mul_f32 v[62:63], v[62:63], v[70:71] op_sel_hi:[1,0]
	v_pk_mul_f32 v[60:61], v[60:61], v[70:71] op_sel_hi:[1,0]
	v_pk_mul_f32 v[58:59], v[58:59], v[70:71] op_sel_hi:[1,0]
	v_pk_mul_f32 v[56:57], v[56:57], v[70:71] op_sel_hi:[1,0]
	v_pk_mul_f32 v[54:55], v[54:55], v[70:71] op_sel_hi:[1,0]
	v_pk_mul_f32 v[52:53], v[52:53], v[70:71] op_sel_hi:[1,0]
	v_pk_mul_f32 v[50:51], v[50:51], v[70:71] op_sel_hi:[1,0]
	s_cbranch_vccnz .LBB0_238
	v_lshlrev_b64 v[70:71], 12, v[66:67]
	v_lshl_add_u64 v[74:75], v[152:153], 0, v[70:71]
	v_cvt_pk_bf16_f32 v70, v62, v63
	v_cvt_pk_bf16_f32 v71, v64, v65
	v_cvt_pk_bf16_f32 v72, v58, v59
	v_cvt_pk_bf16_f32 v73, v60, v61
	s_mov_b64 s[42:43], 0
	global_store_dwordx4 v[74:75], v[70:73], off
	s_nop 1
	v_cvt_pk_bf16_f32 v70, v54, v55
	v_cvt_pk_bf16_f32 v71, v56, v57
	v_cvt_pk_bf16_f32 v72, v50, v51
	v_cvt_pk_bf16_f32 v73, v52, v53
	global_store_dwordx4 v[74:75], v[70:73], off offset:256

;     __device__ __forceinline__ void operator()(const f32x4 (&acc)[2][2][4][2], const Unit& u, int wr, int wc, int fr, int fq) const {
;     ...
;                 const int grow = u.pm * BM + ai * HALF + wr * 64 + m * 16 + fr;
;                 const int pos = NMETA_ + (grow & 4095), srow = (grow >> 12) * TPAD + pos;
;                 const float rr = rs1[grow];
;                 const f32x4 a00 = acc[ai][0][m][0] * rr, a01 = acc[ai][0][m][1] * rr, a10 = acc[ai][1][m][0] * rr, a11 = acc[ai][1][m][1] * rr;
.LBB0_240:
	s_nop 0
	v_or_b32_e32 v50, s17, v163
	v_ashrrev_i32_e32 v51, 31, v50
	v_lshl_add_u64 v[50:51], v[50:51], 2, s[6:7]
	s_nop 0
	v_bitop3_b32 v50, s17, v162, v163 bitop3:0xc8
	v_add_u32_e32 v52, 16, v50
	v_add_u32_e32 v50, s35, v52
	s_mov_b64 s[42:43], -1
	s_and_b64 vcc, exec, s[2:3]
	v_ashrrev_i32_e32 v51, 31, v50
	v_mov_b32_e32 v54, v216
	v_pk_mul_f32 v[48:49], v[48:49], v[54:55] op_sel_hi:[1,0]
	v_pk_mul_f32 v[46:47], v[46:47], v[54:55] op_sel_hi:[1,0]
	v_pk_mul_f32 v[44:45], v[44:45], v[54:55] op_sel_hi:[1,0]
	v_pk_mul_f32 v[42:43], v[42:43], v[54:55] op_sel_hi:[1,0]
	v_pk_mul_f32 v[40:41], v[40:41], v[54:55] op_sel_hi:[1,0]
	v_pk_mul_f32 v[38:39], v[38:39], v[54:55] op_sel_hi:[1,0]
	v_pk_mul_f32 v[36:37], v[36:37], v[54:55] op_sel_hi:[1,0]
	v_pk_mul_f32 v[34:35], v[34:35], v[54:55] op_sel_hi:[1,0]
	s_cbranch_vccnz .LBB0_242
	v_lshlrev_b64 v[54:55], 12, v[50:51]
	v_lshl_add_u64 v[58:59], v[152:153], 0, v[54:55]
	v_cvt_pk_bf16_f32 v54, v46, v47
	v_cvt_pk_bf16_f32 v55, v48, v49
	v_cvt_pk_bf16_f32 v56, v42, v43
	v_cvt_pk_bf16_f32 v57, v44, v45
	s_mov_b64 s[42:43], 0
	global_store_dwordx4 v[58:59], v[54:57], off
	s_nop 1
	v_cvt_pk_bf16_f32 v54, v38, v39
	v_cvt_pk_bf16_f32 v55, v40, v41
	v_cvt_pk_bf16_f32 v56, v34, v35
	v_cvt_pk_bf16_f32 v57, v36, v37
	global_store_dwordx4 v[58:59], v[54:57], off offset:256

;     __device__ __forceinline__ void operator()(const f32x4 (&acc)[2][2][4][2], const Unit& u, int wr, int wc, int fr, int fq) const {
;     ...
;                 const int grow = u.pm * BM + ai * HALF + wr * 64 + m * 16 + fr;
;                 const int pos = NMETA_ + (grow & 4095), srow = (grow >> 12) * TPAD + pos;
;                 const float rr = rs1[grow];
;                 const f32x4 a00 = acc[ai][0][m][0] * rr, a01 = acc[ai][0][m][1] * rr, a10 = acc[ai][1][m][0] * rr, a11 = acc[ai][1][m][1] * rr;
.LBB0_244:
	s_nop 0
	v_or_b32_e32 v34, s17, v165
	v_ashrrev_i32_e32 v35, 31, v34
	v_lshl_add_u64 v[36:37], v[34:35], 2, s[6:7]
	s_nop 0
	v_and_or_b32 v36, v34, s77, 16
	v_add_u32_e32 v34, s35, v36
	s_mov_b64 s[42:43], -1
	s_and_b64 vcc, exec, s[2:3]
	v_ashrrev_i32_e32 v35, 31, v34
	v_mov_b32_e32 v38, v218
	v_pk_mul_f32 v[32:33], v[32:33], v[38:39] op_sel_hi:[1,0]
	v_pk_mul_f32 v[30:31], v[30:31], v[38:39] op_sel_hi:[1,0]
	v_pk_mul_f32 v[28:29], v[28:29], v[38:39] op_sel_hi:[1,0]
	v_pk_mul_f32 v[26:27], v[26:27], v[38:39] op_sel_hi:[1,0]
	v_pk_mul_f32 v[24:25], v[24:25], v[38:39] op_sel_hi:[1,0]
	v_pk_mul_f32 v[22:23], v[22:23], v[38:39] op_sel_hi:[1,0]
	v_pk_mul_f32 v[20:21], v[20:21], v[38:39] op_sel_hi:[1,0]
	v_pk_mul_f32 v[18:19], v[18:19], v[38:39] op_sel_hi:[1,0]
	s_cbranch_vccnz .LBB0_246
	v_lshlrev_b64 v[38:39], 12, v[34:35]
	v_lshl_add_u64 v[42:43], v[152:153], 0, v[38:39]
	v_cvt_pk_bf16_f32 v38, v30, v31
	v_cvt_pk_bf16_f32 v39, v32, v33
	v_cvt_pk_bf16_f32 v40, v26, v27
	v_cvt_pk_bf16_f32 v41, v28, v29
	s_mov_b64 s[42:43], 0
	global_store_dwordx4 v[42:43], v[38:41], off
	s_nop 1
	v_cvt_pk_bf16_f32 v38, v22, v23
	v_cvt_pk_bf16_f32 v39, v24, v25
	v_cvt_pk_bf16_f32 v40, v18, v19
	v_cvt_pk_bf16_f32 v41, v20, v21
	global_store_dwordx4 v[42:43], v[38:41], off offset:256

;     __device__ __forceinline__ void operator()(const f32x4 (&acc)[2][2][4][2], const Unit& u, int wr, int wc, int fr, int fq) const {
;     ...
;                 const int grow = u.pm * BM + ai * HALF + wr * 64 + m * 16 + fr;
;                 const int pos = NMETA_ + (grow & 4095), srow = (grow >> 12) * TPAD + pos;
;                 const float rr = rs1[grow];
;                 const f32x4 a00 = acc[ai][0][m][0] * rr, a01 = acc[ai][0][m][1] * rr, a10 = acc[ai][1][m][0] * rr, a11 = acc[ai][1][m][1] * rr;
.LBB0_248:
	s_nop 0
	v_or_b32_e32 v18, s17, v166
	v_ashrrev_i32_e32 v19, 31, v18
	v_lshl_add_u64 v[18:19], v[18:19], 2, s[6:7]
	s_nop 0
	v_bitop3_b32 v18, s17, v167, v166 bitop3:0xc8
	v_add_u32_e32 v20, 16, v18
	v_add_u32_e32 v18, s35, v20
	s_mov_b64 s[42:43], -1
	s_and_b64 vcc, exec, s[2:3]
	v_ashrrev_i32_e32 v19, 31, v18
	v_mov_b32_e32 v22, v220
	v_pk_mul_f32 v[16:17], v[16:17], v[22:23] op_sel_hi:[1,0]
	v_pk_mul_f32 v[14:15], v[14:15], v[22:23] op_sel_hi:[1,0]
	v_pk_mul_f32 v[12:13], v[12:13], v[22:23] op_sel_hi:[1,0]
	v_pk_mul_f32 v[10:11], v[10:11], v[22:23] op_sel_hi:[1,0]
	v_pk_mul_f32 v[8:9], v[8:9], v[22:23] op_sel_hi:[1,0]
	v_pk_mul_f32 v[6:7], v[6:7], v[22:23] op_sel_hi:[1,0]
	v_pk_mul_f32 v[4:5], v[4:5], v[22:23] op_sel_hi:[1,0]
	v_pk_mul_f32 v[2:3], v[2:3], v[22:23] op_sel_hi:[1,0]
	s_cbranch_vccz .LBB0_251
	s_andn2_b64 vcc, exec, s[42:43]
	s_cbranch_vccz .LBB0_252

; __device__ __forceinline__ KP kargs() { KP q = (KP)__builtin_amdgcn_kernarg_segment_ptr(); asm volatile("" : "+s"(q)); return q; }
; __global__ void __launch_bounds__(512, 2) fwd_mega(Params P_by_kernarg) {
;     ...
;     if (IN(5)) {
;         const KP KA = kargs(); unsigned char* const ws = KA->ws;
;         for (int row = gw; row < MX; row += 2 * NGW) {
;             const int rB = (row + NGW < MX) ? row + NGW : row; const bool hasB = row + NGW < MX;
;             const float sA = ssq1[(size_t)row * 64 + lane], sB = ssq1[(size_t)rB * 64 + lane];
;             u32x2 xa[16], xb[16], ma[16], mb[16];
;             { const u32x2* m4 = (const u32x2*)(Mixed + (size_t)row * DM) + lane; const u32x2* x4 = (const u32x2*)(Ubuf + (size_t)row * DM) + lane;
; #pragma unroll
;               for (int j = 0; j < 16; ++j) { xa[j] = x4[64 * j]; ma[j] = m4[64 * j]; } }
;             { const u32x2* m4 = (const u32x2*)(Mixed + (size_t)rB * DM) + lane; const u32x2* x4 = (const u32x2*)(Ubuf + (size_t)rB * DM) + lane;
; #pragma unroll
;               for (int j = 0; j < 16; ++j) { xb[j] = x4[64 * j]; mb[j] = m4[64 * j]; } }
;             const f32x4* gp = (const f32x4*)KA->in[17] + lane;
.LBB0_796:
.LBB0_797:
	s_cmp_lt_i32 s33, 6
	s_cselect_b64 s[4:5], -1, 0
	s_and_b64 s[4:5], s[4:5], s[2:3]
	s_andn2_b64 vcc, exec, s[4:5]
	s_cbranch_vccnz .LBB0_807
	s_mov_b64 s[2:3], s[0:1]
	s_cmpk_gt_i32 s18, 0x1fff
	s_cbranch_scc1 .LBB0_807
	s_waitcnt vmcnt(0)
	v_mbcnt_lo_u32_b32 v14, -1, 0
	v_mbcnt_hi_u32_b32 v14, -1, v14
	v_and_b32_e32 v15, 64, v14
	v_add_u32_e32 v15, 64, v15
	v_xor_b32_e32 v16, 1, v14
	v_cmp_lt_i32_e32 vcc, v16, v15
	s_load_dwordx2 s[6:7], s[2:3], 0xc0
	s_load_dwordx2 s[8:9], s[2:3], 0x88
	v_cndmask_b32_e32 v16, v14, v16, vcc
	v_lshlrev_b32_e32 v174, 2, v16
	v_xor_b32_e32 v16, 2, v14
	v_cmp_lt_i32_e32 vcc, v16, v15
	v_mov_b32_e32 v3, 0
	v_lshlrev_b32_e32 v10, 4, v196
	v_cndmask_b32_e32 v16, v14, v16, vcc
	v_lshlrev_b32_e32 v175, 2, v16
	v_xor_b32_e32 v16, 4, v14
	v_cmp_lt_i32_e32 vcc, v16, v15
	v_mov_b32_e32 v11, v3
	s_waitcnt lgkmcnt(0)
	v_lshl_add_u64 v[10:11], s[8:9], 0, v[10:11]
	v_cndmask_b32_e32 v16, v14, v16, vcc
	v_lshlrev_b32_e32 v176, 2, v16
	v_xor_b32_e32 v16, 8, v14
	v_cmp_lt_i32_e32 vcc, v16, v15
	s_mov_b64 s[10:11], 0x1000
	s_add_u32 s21, s6, 0x18710000
	v_cndmask_b32_e32 v16, v14, v16, vcc
	v_lshlrev_b32_e32 v177, 2, v16
	v_xor_b32_e32 v16, 16, v14
	v_cmp_lt_i32_e32 vcc, v16, v15
	s_addc_u32 s40, s7, 0
	s_ashr_i32 s19, s18, 31
	v_cndmask_b32_e32 v16, v14, v16, vcc
	v_lshlrev_b32_e32 v178, 2, v16
	v_xor_b32_e32 v16, 32, v14
	v_cmp_lt_i32_e32 vcc, v16, v15
	v_lshlrev_b32_e32 v38, 3, v196
	v_mov_b32_e32 v39, v3
	v_cndmask_b32_e32 v14, v14, v16, vcc
	v_lshlrev_b32_e32 v179, 2, v14
	v_lshl_add_u64 v[14:15], v[10:11], 0, s[10:11]
	s_mov_b64 s[10:11], 0x1400
	v_lshl_add_u64 v[16:17], v[10:11], 0, s[10:11]
	s_mov_b64 s[10:11], 0x1800
	v_lshl_add_u64 v[18:19], v[10:11], 0, s[10:11]
	s_mov_b64 s[10:11], 0x1c00
	v_lshl_add_u64 v[20:21], v[10:11], 0, s[10:11]
	s_mov_b64 s[10:11], 0x2000
	v_lshl_add_u64 v[22:23], v[10:11], 0, s[10:11]
	s_mov_b64 s[10:11], 0x2400
	v_lshl_add_u64 v[24:25], v[10:11], 0, s[10:11]
	s_mov_b64 s[10:11], 0x2800
	v_lshl_add_u64 v[26:27], v[10:11], 0, s[10:11]
	s_mov_b64 s[10:11], 0x2c00
	v_lshl_add_u64 v[28:29], v[10:11], 0, s[10:11]
	s_mov_b64 s[10:11], 0x3000
	v_lshl_add_u64 v[30:31], v[10:11], 0, s[10:11]
	s_mov_b64 s[10:11], 0x3400
	v_lshl_add_u64 v[32:33], v[10:11], 0, s[10:11]
	s_mov_b64 s[10:11], 0x3800
	v_lshl_add_u64 v[34:35], v[10:11], 0, s[10:11]
	s_mov_b64 s[10:11], 0x3c00
	s_lshl_b32 s8, s22, 4
	v_lshl_add_u64 v[36:37], v[10:11], 0, s[10:11]
	s_lshl_b64 s[10:11], s[18:19], 2
	v_lshl_add_u64 v[12:13], s[6:7], 0, v[38:39]
	s_mov_b64 s[2:3], 0x27e00000
	s_add_u32 s41, s10, 0x18710000
	v_lshlrev_b32_e32 v2, 2, v196
	v_lshl_add_u64 v[6:7], v[12:13], 0, s[2:3]
	s_mov_b64 s[2:3], 0x19000000
	s_addc_u32 s42, s11, 0
	s_lshl_b64 s[34:35], s[18:19], 8
	v_lshl_add_u64 v[4:5], s[6:7], 0, v[2:3]
	s_mov_b64 s[16:17], 0x18800000
	v_lshl_add_u64 v[8:9], v[12:13], 0, s[2:3]
	s_mov_b64 s[2:3], 0x30200000
	s_ashr_i32 s9, s8, 31
	s_lshl_b64 s[12:13], s[18:19], 13
	v_or_b32_e32 v40, s34, v2
	v_mov_b32_e32 v41, s35
	v_lshl_add_u64 v[4:5], v[4:5], 0, s[16:17]
	v_lshl_add_u64 v[12:13], v[12:13], 0, s[2:3]
	v_cmp_eq_u32_e64 s[2:3], 0, v196
	s_lshl_b64 s[10:11], s[8:9], 2
	v_or_b32_e32 v38, s12, v38
	v_mov_b32_e32 v39, s13
	s_lshl_b64 s[12:13], s[8:9], 13
	v_lshl_add_u64 v[40:41], v[40:41], 0, s[16:17]
	s_lshl_b64 s[16:17], s[8:9], 8
	s_mov_b32 s9, 0x19000000
	s_mov_b32 s19, 0x27e00000
	s_mov_b32 s43, 0x19001000
	s_mov_b32 s44, 0x27e01000
	s_movk_i32 s45, 0x1000
	v_mov_b32_e32 v180, 0x358637bd
	s_mov_b32 s46, 0x800000
	s_mov_b32 s47, 0x30200000
	s_mov_b32 s48, 0x30201000
	s_mov_b32 s49, s18
	global_load_dwordx2 v[194:195], v[10:11], off offset:1024
	global_load_dwordx2 v[198:199], v[10:11], off offset:1032
	global_load_dwordx4 v[200:203], v[10:11], off offset:2048
	global_load_dwordx4 v[204:207], v[10:11], off offset:3072
	global_load_dwordx4 v[208:211], v[14:15], off
	global_load_dwordx4 v[212:215], v[16:17], off
	global_load_dwordx4 v[216:219], v[18:19], off
	global_load_dwordx4 v[220:223], v[20:21], off
	global_load_dwordx4 v[224:227], v[22:23], off
	global_load_dwordx4 v[228:231], v[24:25], off
	global_load_dwordx4 v[232:235], v[26:27], off
	global_load_dwordx4 v[236:239], v[28:29], off
	global_load_dwordx4 v[240:243], v[30:31], off
	global_load_dwordx4 v[244:247], v[32:33], off
	global_load_dwordx4 v[248:251], v[34:35], off
	global_load_dwordx4 v[252:255], v[36:37], off
	s_branch .LBB0_802

; __global__ void __launch_bounds__(512, 2) fwd_mega(Params P_by_kernarg) {
;     ...
;         for (int row = gw; row < MX; row += 2 * NGW) {
;             const int rB = (row + NGW < MX) ? row + NGW : row; const bool hasB = row + NGW < MX;
;             const float sA = ssq1[(size_t)row * 64 + lane], sB = ssq1[(size_t)rB * 64 + lane];
;             u32x2 xa[16], xb[16], ma[16], mb[16];
;             { const u32x2* m4 = (const u32x2*)(Mixed + (size_t)row * DM) + lane; const u32x2* x4 = (const u32x2*)(Ubuf + (size_t)row * DM) + lane;
; #pragma unroll
;               for (int j = 0; j < 16; ++j) { xa[j] = x4[64 * j]; ma[j] = m4[64 * j]; } }
;             { const u32x2* m4 = (const u32x2*)(Mixed + (size_t)rB * DM) + lane; const u32x2* x4 = (const u32x2*)(Ubuf + (size_t)rB * DM) + lane;
; #pragma unroll
;               for (int j = 0; j < 16; ++j) { xb[j] = x4[64 * j]; mb[j] = m4[64 * j]; } }
;             const f32x4* gp = (const f32x4*)KA->in[17] + lane;
.LBB0_802:
	s_waitcnt lgkmcnt(0)
	v_lshl_add_u64 v[42:43], s[6:7], 0, v[40:41]
	global_load_dword v2, v[42:43], off
	global_load_dwordx4 v[130:133], v[10:11], off
	v_lshl_add_u64 v[124:125], s[6:7], 0, v[38:39]
	v_add_co_u32_e32 v42, vcc, s9, v124
	s_add_i32 s38, s20, s49
	s_nop 0
	v_addc_co_u32_e32 v43, vcc, 0, v125, vcc
	v_add_co_u32_e32 v44, vcc, s43, v124
	s_cmpk_lt_i32 s38, 0x2000
	s_nop 0
	v_addc_co_u32_e32 v45, vcc, 0, v125, vcc
	v_add_co_u32_e32 v46, vcc, s19, v124
	s_cselect_b64 s[36:37], -1, 0
	s_nop 0
	v_addc_co_u32_e32 v47, vcc, 0, v125, vcc
	v_add_co_u32_e32 v48, vcc, s44, v124
	s_and_b64 s[34:35], s[36:37], exec
	s_nop 0
	v_addc_co_u32_e32 v49, vcc, 0, v125, vcc
	global_load_dwordx2 v[106:107], v[48:49], off offset:-4096
	global_load_dwordx2 v[140:141], v[42:43], off offset:1536
	global_load_dwordx2 v[148:149], v[42:43], off offset:2048
	global_load_dwordx2 v[156:157], v[42:43], off offset:2560
	global_load_dwordx2 v[164:165], v[42:43], off offset:3072
	global_load_dwordx2 v[134:135], v[46:47], off offset:512
	global_load_dwordx2 v[142:143], v[46:47], off offset:1024
	global_load_dwordx2 v[186:187], v[46:47], off offset:1536
	global_load_dwordx2 v[168:169], v[42:43], off offset:3584
	global_load_dwordx2 v[150:151], v[46:47], off offset:2048
	global_load_dwordx2 v[158:159], v[46:47], off offset:2560
	global_load_dwordx2 v[166:167], v[46:47], off offset:3072
	global_load_dwordx2 v[170:171], v[46:47], off offset:3584
	global_load_dwordx2 v[116:117], v[44:45], off offset:-4096
	global_load_dwordx2 v[160:161], v[44:45], off
	global_load_dwordx2 v[152:153], v[44:45], off offset:512
	global_load_dwordx2 v[144:145], v[44:45], off offset:1024
	global_load_dwordx2 v[146:147], v[48:49], off offset:1024
	global_load_dwordx2 v[138:139], v[48:49], off offset:1536
	global_load_dwordx2 v[128:129], v[48:49], off offset:2048
	global_load_dwordx2 v[122:123], v[48:49], off offset:2560
	global_load_dwordx2 v[136:137], v[44:45], off offset:1536
	global_load_dwordx2 v[126:127], v[44:45], off offset:2048
	global_load_dwordx2 v[120:121], v[44:45], off offset:2560
	global_load_dwordx2 v[112:113], v[44:45], off offset:3072
	global_load_dwordx2 v[162:163], v[48:49], off
	global_load_dwordx2 v[154:155], v[48:49], off offset:512
	global_load_dwordx2 v[108:109], v[44:45], off offset:3584
	global_load_dwordx2 v[114:115], v[48:49], off offset:3072
	global_load_dwordx2 v[110:111], v[48:49], off offset:3584
	s_cselect_b32 s34, s38, s49
	s_ashr_i32 s35, s34, 31
	s_lshl_b64 s[38:39], s[34:35], 8
	s_lshl_b64 s[50:51], s[34:35], 13
	v_lshl_add_u64 v[44:45], v[4:5], 0, s[38:39]
	v_lshl_add_u64 v[46:47], v[6:7], 0, s[50:51]
	v_lshl_add_u64 v[48:49], v[8:9], 0, s[50:51]
	global_load_dword v181, v[44:45], off
	global_load_dwordx2 v[182:183], v[42:43], off offset:512
	global_load_dwordx2 v[188:189], v[42:43], off offset:1024
	global_load_dwordx2 v[102:103], v[48:49], off
	global_load_dwordx2 v[98:99], v[48:49], off offset:512
	global_load_dwordx2 v[94:95], v[48:49], off offset:1024
	global_load_dwordx2 v[90:91], v[48:49], off offset:1536
	global_load_dwordx2 v[104:105], v[46:47], off
	global_load_dwordx2 v[100:101], v[46:47], off offset:512
	global_load_dwordx2 v[96:97], v[46:47], off offset:1024
	global_load_dwordx2 v[92:93], v[46:47], off offset:1536
	global_load_dwordx2 v[86:87], v[48:49], off offset:2048
	global_load_dwordx2 v[82:83], v[48:49], off offset:2560
	global_load_dwordx2 v[78:79], v[48:49], off offset:3072
	global_load_dwordx2 v[74:75], v[48:49], off offset:3584
	global_load_dwordx2 v[88:89], v[46:47], off offset:2048
	global_load_dwordx2 v[84:85], v[46:47], off offset:2560
	global_load_dwordx2 v[80:81], v[46:47], off offset:3072
	global_load_dwordx2 v[76:77], v[46:47], off offset:3584
	v_add_co_u32_e32 v42, vcc, s45, v48
	s_waitcnt vmcnt(48)
	v_and_b32_e32 v119, 0xffff0000, v106
	v_addc_co_u32_e32 v43, vcc, 0, v49, vcc
	global_load_dwordx2 v[70:71], v[42:43], off
	global_load_dwordx2 v[66:67], v[42:43], off offset:512
	global_load_dwordx2 v[62:63], v[42:43], off offset:1024
	global_load_dwordx2 v[58:59], v[42:43], off offset:1536
	ds_bpermute_b32 v44, v174, v2
	s_waitcnt lgkmcnt(0)
	v_add_f32_e32 v2, v2, v44
	ds_bpermute_b32 v48, v175, v2
	v_add_co_u32_e32 v44, vcc, s45, v46
	s_waitcnt vmcnt(39)
	v_and_b32_e32 v173, 0xffff0000, v116
	v_addc_co_u32_e32 v45, vcc, 0, v47, vcc
	s_waitcnt lgkmcnt(0)
	v_add_f32_e32 v2, v2, v48
	ds_bpermute_b32 v46, v176, v2
	global_load_dwordx2 v[72:73], v[44:45], off
	global_load_dwordx2 v[68:69], v[44:45], off offset:512
	global_load_dwordx2 v[64:65], v[44:45], off offset:1024
	global_load_dwordx2 v[60:61], v[44:45], off offset:1536
	s_waitcnt vmcnt(25)
	v_lshlrev_b32_e32 v184, 16, v182
	v_and_b32_e32 v185, 0xffff0000, v182
	v_lshlrev_b32_e32 v182, 16, v183
	s_waitcnt lgkmcnt(0)
	v_add_f32_e32 v2, v2, v46
	ds_bpermute_b32 v46, v177, v2
	v_and_b32_e32 v183, 0xffff0000, v183
	v_lshlrev_b32_e32 v192, 16, v109
	v_and_b32_e32 v193, 0xffff0000, v109
	s_waitcnt lgkmcnt(0)
	v_add_f32_e32 v2, v2, v46
	ds_bpermute_b32 v48, v178, v2
	global_load_dwordx2 v[54:55], v[42:43], off offset:2048
	global_load_dwordx2 v[50:51], v[42:43], off offset:2560
	global_load_dwordx2 v[46:47], v[42:43], off offset:3072
	s_nop 0
	global_load_dwordx2 v[42:43], v[42:43], off offset:3584
	s_waitcnt lgkmcnt(0)
	v_add_f32_e32 v2, v2, v48
	ds_bpermute_b32 v118, v179, v2
	global_load_dwordx2 v[56:57], v[44:45], off offset:2048
	global_load_dwordx2 v[52:53], v[44:45], off offset:2560
	global_load_dwordx2 v[48:49], v[44:45], off offset:3072
	s_nop 0
	global_load_dwordx2 v[44:45], v[44:45], off offset:3584
	s_waitcnt lgkmcnt(0)
	v_add_f32_e32 v2, v2, v118
	v_fmamk_f32 v2, v2, 0x39800000, v180
	v_mul_f32_e32 v118, 0x4b800000, v2
	v_cmp_gt_f32_e32 vcc, s46, v2
	s_nop 1
	v_cndmask_b32_e32 v2, v2, v118, vcc
	v_rsq_f32_e32 v2, v2
	v_lshlrev_b32_e32 v118, 16, v106
	v_lshlrev_b32_e32 v106, 16, v107
	v_and_b32_e32 v107, 0xffff0000, v107
	v_mul_f32_e32 v172, 0x45800000, v2
	v_cndmask_b32_e32 v2, v2, v172, vcc
	v_lshlrev_b32_e32 v172, 16, v116
	v_lshlrev_b32_e32 v116, 16, v117
	v_and_b32_e32 v117, 0xffff0000, v117
	v_pk_mul_f32 v[106:107], v[2:3], v[106:107] op_sel_hi:[0,1]
	v_pk_fma_f32 v[116:117], v[132:133], v[106:107], v[116:117]
	v_add_co_u32_e32 v106, vcc, s48, v124
	v_pk_mul_f32 v[118:119], v[2:3], v[118:119] op_sel_hi:[0,1]
	s_nop 0
	v_addc_co_u32_e32 v107, vcc, 0, v125, vcc
	v_pk_fma_f32 v[118:119], v[130:131], v[118:119], v[172:173]
	v_add_co_u32_e32 v172, vcc, s47, v124
	v_cvt_pk_bf16_f32 v130, v118, v119
	v_cvt_pk_bf16_f32 v131, v116, v117
	s_waitcnt vmcnt(0)
	global_store_dwordx2 v[106:107], v[130:131], off offset:-4096
	s_nop 1
	v_addc_co_u32_e32 v173, vcc, 0, v125, vcc
	v_lshlrev_b32_e32 v124, 16, v134
	v_and_b32_e32 v125, 0xffff0000, v134
	v_lshlrev_b32_e32 v134, 16, v135
	v_and_b32_e32 v135, 0xffff0000, v135
	v_pk_mul_f32 v[190:191], v[2:3], v[124:125] op_sel_hi:[0,1]
	v_pk_mul_f32 v[124:125], v[2:3], v[134:135] op_sel_hi:[0,1]
	v_lshlrev_b32_e32 v134, 16, v143
	v_and_b32_e32 v135, 0xffff0000, v143
	v_and_b32_e32 v143, 0xffff0000, v188
	v_pk_fma_f32 v[124:125], v[198:199], v[124:125], v[182:183]
	v_pk_fma_f32 v[130:131], v[194:195], v[190:191], v[184:185]
	s_nop 0
	v_cvt_pk_bf16_f32 v132, v130, v131
	v_cvt_pk_bf16_f32 v133, v124, v125
	global_store_dwordx2 v[172:173], v[132:133], off offset:512
	s_nop 1
	v_lshlrev_b32_e32 v132, 16, v142
	v_and_b32_e32 v133, 0xffff0000, v142
	v_lshlrev_b32_e32 v142, 16, v188
	v_lshlrev_b32_e32 v188, 16, v189
	v_and_b32_e32 v189, 0xffff0000, v189
	v_pk_mul_f32 v[190:191], v[2:3], v[132:133] op_sel_hi:[0,1]
	v_pk_mul_f32 v[132:133], v[2:3], v[134:135] op_sel_hi:[0,1]
	v_pk_fma_f32 v[132:133], v[202:203], v[132:133], v[188:189]
	v_pk_fma_f32 v[134:135], v[200:201], v[190:191], v[142:143]
	v_lshlrev_b32_e32 v188, 16, v140
	v_cvt_pk_bf16_f32 v142, v134, v135
	v_cvt_pk_bf16_f32 v143, v132, v133
	global_store_dwordx2 v[172:173], v[142:143], off offset:1024
	s_nop 1
	v_lshlrev_b32_e32 v142, 16, v186
	v_and_b32_e32 v143, 0xffff0000, v186
	v_lshlrev_b32_e32 v186, 16, v187
	v_and_b32_e32 v187, 0xffff0000, v187
	v_and_b32_e32 v189, 0xffff0000, v140
	v_lshlrev_b32_e32 v140, 16, v141
	v_and_b32_e32 v141, 0xffff0000, v141
	v_pk_mul_f32 v[142:143], v[2:3], v[142:143] op_sel_hi:[0,1]
	v_pk_mul_f32 v[186:187], v[2:3], v[186:187] op_sel_hi:[0,1]
	v_lshlrev_b32_e32 v190, 16, v108
	v_and_b32_e32 v191, 0xffff0000, v108
	v_pk_fma_f32 v[140:141], v[206:207], v[186:187], v[140:141]
	v_pk_fma_f32 v[142:143], v[204:205], v[142:143], v[188:189]
	v_lshlrev_b32_e32 v186, 16, v150
	v_cvt_pk_bf16_f32 v182, v142, v143
	v_cvt_pk_bf16_f32 v183, v140, v141
	global_store_dwordx2 v[172:173], v[182:183], off offset:1536
	s_nop 1
	v_and_b32_e32 v187, 0xffff0000, v150
	v_lshlrev_b32_e32 v150, 16, v151
	v_and_b32_e32 v151, 0xffff0000, v151
	v_lshlrev_b32_e32 v188, 16, v148
	v_and_b32_e32 v189, 0xffff0000, v148
	v_lshlrev_b32_e32 v148, 16, v149
	v_and_b32_e32 v149, 0xffff0000, v149
	v_pk_mul_f32 v[186:187], v[2:3], v[186:187] op_sel_hi:[0,1]
	v_pk_mul_f32 v[150:151], v[2:3], v[150:151] op_sel_hi:[0,1]
	v_pk_fma_f32 v[148:149], v[210:211], v[150:151], v[148:149]
	v_pk_fma_f32 v[150:151], v[208:209], v[186:187], v[188:189]
	v_lshlrev_b32_e32 v186, 16, v158
	v_cvt_pk_bf16_f32 v182, v150, v151
	v_cvt_pk_bf16_f32 v183, v148, v149
	global_store_dwordx2 v[172:173], v[182:183], off offset:2048
	s_nop 1
	v_and_b32_e32 v187, 0xffff0000, v158
	v_lshlrev_b32_e32 v158, 16, v159
	v_and_b32_e32 v159, 0xffff0000, v159
	v_lshlrev_b32_e32 v188, 16, v156
	v_and_b32_e32 v189, 0xffff0000, v156
	v_lshlrev_b32_e32 v156, 16, v157
	v_and_b32_e32 v157, 0xffff0000, v157
	v_pk_mul_f32 v[186:187], v[2:3], v[186:187] op_sel_hi:[0,1]
	v_pk_mul_f32 v[158:159], v[2:3], v[158:159] op_sel_hi:[0,1]
	v_pk_fma_f32 v[156:157], v[214:215], v[158:159], v[156:157]
	v_pk_fma_f32 v[158:159], v[212:213], v[186:187], v[188:189]
	v_lshlrev_b32_e32 v186, 16, v166
	v_cvt_pk_bf16_f32 v182, v158, v159
	v_cvt_pk_bf16_f32 v183, v156, v157
	global_store_dwordx2 v[172:173], v[182:183], off offset:2560
	s_nop 1
	v_and_b32_e32 v187, 0xffff0000, v166
	v_lshlrev_b32_e32 v166, 16, v167
	v_and_b32_e32 v167, 0xffff0000, v167
	v_lshlrev_b32_e32 v188, 16, v164
	v_and_b32_e32 v189, 0xffff0000, v164
	v_lshlrev_b32_e32 v164, 16, v165
	v_and_b32_e32 v165, 0xffff0000, v165
	v_pk_mul_f32 v[186:187], v[2:3], v[186:187] op_sel_hi:[0,1]
	v_pk_mul_f32 v[166:167], v[2:3], v[166:167] op_sel_hi:[0,1]
	v_pk_fma_f32 v[164:165], v[218:219], v[166:167], v[164:165]
	v_pk_fma_f32 v[166:167], v[216:217], v[186:187], v[188:189]
	v_lshlrev_b32_e32 v186, 16, v170
	v_cvt_pk_bf16_f32 v182, v166, v167
	v_cvt_pk_bf16_f32 v183, v164, v165
	global_store_dwordx2 v[172:173], v[182:183], off offset:3072
	s_nop 1
	v_and_b32_e32 v187, 0xffff0000, v170
	v_lshlrev_b32_e32 v170, 16, v171
	v_and_b32_e32 v171, 0xffff0000, v171
	v_lshlrev_b32_e32 v188, 16, v168
	v_and_b32_e32 v189, 0xffff0000, v168
	v_lshlrev_b32_e32 v168, 16, v169
	v_and_b32_e32 v169, 0xffff0000, v169
	v_pk_mul_f32 v[186:187], v[2:3], v[186:187] op_sel_hi:[0,1]
	v_pk_mul_f32 v[170:171], v[2:3], v[170:171] op_sel_hi:[0,1]
	v_pk_fma_f32 v[168:169], v[222:223], v[170:171], v[168:169]
	v_pk_fma_f32 v[170:171], v[220:221], v[186:187], v[188:189]
	v_lshlrev_b32_e32 v186, 16, v160
	v_cvt_pk_bf16_f32 v182, v170, v171
	v_cvt_pk_bf16_f32 v183, v168, v169
	global_store_dwordx2 v[172:173], v[182:183], off offset:3584
	s_nop 1
	v_lshlrev_b32_e32 v172, 16, v162
	v_and_b32_e32 v173, 0xffff0000, v162
	v_lshlrev_b32_e32 v162, 16, v163
	v_and_b32_e32 v163, 0xffff0000, v163
	v_and_b32_e32 v187, 0xffff0000, v160
	v_lshlrev_b32_e32 v160, 16, v161
	v_and_b32_e32 v161, 0xffff0000, v161
	v_pk_mul_f32 v[172:173], v[2:3], v[172:173] op_sel_hi:[0,1]
	v_pk_mul_f32 v[162:163], v[2:3], v[162:163] op_sel_hi:[0,1]
	v_lshlrev_b32_e32 v188, 16, v110
	v_and_b32_e32 v189, 0xffff0000, v110
	v_lshlrev_b32_e32 v110, 16, v111
	v_and_b32_e32 v111, 0xffff0000, v111
	v_pk_fma_f32 v[160:161], v[226:227], v[162:163], v[160:161]
	v_pk_fma_f32 v[162:163], v[224:225], v[172:173], v[186:187]
	v_lshlrev_b32_e32 v186, 16, v152
	v_cvt_pk_bf16_f32 v172, v162, v163
	v_cvt_pk_bf16_f32 v173, v160, v161
	global_store_dwordx2 v[106:107], v[172:173], off
	s_nop 1
	v_lshlrev_b32_e32 v172, 16, v154
	v_and_b32_e32 v173, 0xffff0000, v154
	v_lshlrev_b32_e32 v154, 16, v155
	v_and_b32_e32 v155, 0xffff0000, v155
	v_and_b32_e32 v187, 0xffff0000, v152
	v_lshlrev_b32_e32 v152, 16, v153
	v_and_b32_e32 v153, 0xffff0000, v153
	v_pk_mul_f32 v[172:173], v[2:3], v[172:173] op_sel_hi:[0,1]
	v_pk_mul_f32 v[154:155], v[2:3], v[154:155] op_sel_hi:[0,1]
	v_pk_fma_f32 v[152:153], v[230:231], v[154:155], v[152:153]
	v_pk_fma_f32 v[154:155], v[228:229], v[172:173], v[186:187]
	v_lshlrev_b32_e32 v186, 16, v144
	v_cvt_pk_bf16_f32 v172, v154, v155
	v_cvt_pk_bf16_f32 v173, v152, v153
	global_store_dwordx2 v[106:107], v[172:173], off offset:512
	s_nop 1
	v_lshlrev_b32_e32 v172, 16, v146
	v_and_b32_e32 v173, 0xffff0000, v146
	v_lshlrev_b32_e32 v146, 16, v147
	v_and_b32_e32 v147, 0xffff0000, v147
	v_and_b32_e32 v187, 0xffff0000, v144
	v_lshlrev_b32_e32 v144, 16, v145
	v_and_b32_e32 v145, 0xffff0000, v145
	v_pk_mul_f32 v[172:173], v[2:3], v[172:173] op_sel_hi:[0,1]
	v_pk_mul_f32 v[146:147], v[2:3], v[146:147] op_sel_hi:[0,1]
	v_pk_fma_f32 v[144:145], v[234:235], v[146:147], v[144:145]
	v_pk_fma_f32 v[146:147], v[232:233], v[172:173], v[186:187]
	v_lshlrev_b32_e32 v186, 16, v136
	v_cvt_pk_bf16_f32 v172, v146, v147
	v_cvt_pk_bf16_f32 v173, v144, v145
	global_store_dwordx2 v[106:107], v[172:173], off offset:1024
	s_nop 1
	v_lshlrev_b32_e32 v172, 16, v138
	v_and_b32_e32 v173, 0xffff0000, v138
	v_lshlrev_b32_e32 v138, 16, v139
	v_and_b32_e32 v139, 0xffff0000, v139
	v_and_b32_e32 v187, 0xffff0000, v136
	v_lshlrev_b32_e32 v136, 16, v137
	v_and_b32_e32 v137, 0xffff0000, v137
	v_pk_mul_f32 v[172:173], v[2:3], v[172:173] op_sel_hi:[0,1]
	v_pk_mul_f32 v[138:139], v[2:3], v[138:139] op_sel_hi:[0,1]
	v_pk_fma_f32 v[136:137], v[238:239], v[138:139], v[136:137]
	v_pk_fma_f32 v[138:139], v[236:237], v[172:173], v[186:187]
	v_lshlrev_b32_e32 v186, 16, v126
	v_cvt_pk_bf16_f32 v172, v138, v139
	v_cvt_pk_bf16_f32 v173, v136, v137
	global_store_dwordx2 v[106:107], v[172:173], off offset:1536
	s_nop 1
	v_lshlrev_b32_e32 v172, 16, v128
	v_and_b32_e32 v173, 0xffff0000, v128
	v_lshlrev_b32_e32 v128, 16, v129
	v_and_b32_e32 v129, 0xffff0000, v129
	v_and_b32_e32 v187, 0xffff0000, v126
	v_lshlrev_b32_e32 v126, 16, v127
	v_and_b32_e32 v127, 0xffff0000, v127
	v_pk_mul_f32 v[172:173], v[2:3], v[172:173] op_sel_hi:[0,1]
	v_pk_mul_f32 v[128:129], v[2:3], v[128:129] op_sel_hi:[0,1]
	v_pk_fma_f32 v[184:185], v[242:243], v[128:129], v[126:127]
	v_pk_fma_f32 v[172:173], v[240:241], v[172:173], v[186:187]
	v_lshlrev_b32_e32 v182, 16, v122
	v_cvt_pk_bf16_f32 v126, v172, v173
	v_cvt_pk_bf16_f32 v127, v184, v185
	global_store_dwordx2 v[106:107], v[126:127], off offset:2048
	s_nop 1
	v_and_b32_e32 v183, 0xffff0000, v122
	v_lshlrev_b32_e32 v122, 16, v123
	v_and_b32_e32 v123, 0xffff0000, v123
	v_lshlrev_b32_e32 v186, 16, v120
	v_and_b32_e32 v187, 0xffff0000, v120
	v_lshlrev_b32_e32 v120, 16, v121
	v_and_b32_e32 v121, 0xffff0000, v121
	v_pk_mul_f32 v[182:183], v[2:3], v[182:183] op_sel_hi:[0,1]
	v_pk_mul_f32 v[122:123], v[2:3], v[122:123] op_sel_hi:[0,1]
	v_pk_fma_f32 v[128:129], v[246:247], v[122:123], v[120:121]
	v_pk_fma_f32 v[126:127], v[244:245], v[182:183], v[186:187]
	v_lshlrev_b32_e32 v182, 16, v114
	v_cvt_pk_bf16_f32 v120, v126, v127
	v_cvt_pk_bf16_f32 v121, v128, v129
	global_store_dwordx2 v[106:107], v[120:121], off offset:2560
	s_nop 1
	v_and_b32_e32 v183, 0xffff0000, v114
	v_lshlrev_b32_e32 v114, 16, v115
	v_and_b32_e32 v115, 0xffff0000, v115
	v_pk_mul_f32 v[108:109], v[2:3], v[182:183] op_sel_hi:[0,1]
	v_pk_mul_f32 v[114:115], v[2:3], v[114:115] op_sel_hi:[0,1]
	v_pk_mul_f32 v[182:183], v[2:3], v[188:189] op_sel_hi:[0,1]
	v_pk_mul_f32 v[188:189], v[2:3], v[110:111] op_sel_hi:[0,1]
	v_mul_f32_e32 v2, v119, v119
	v_mul_f32_e32 v110, v117, v117
	v_fmac_f32_e32 v2, v118, v118
	v_fmac_f32_e32 v110, v116, v116
	v_lshlrev_b32_e32 v186, 16, v112
	v_and_b32_e32 v187, 0xffff0000, v112
	v_lshlrev_b32_e32 v112, 16, v113
	v_and_b32_e32 v113, 0xffff0000, v113
	v_add_f32_e32 v2, v2, v110
	v_mul_f32_e32 v110, v131, v131
	v_mul_f32_e32 v111, v125, v125
	v_fmac_f32_e32 v110, v130, v130
	v_fmac_f32_e32 v111, v124, v124
	v_add_f32_e32 v116, v110, v111
	v_add_f32_e32 v2, v2, v116
	v_mul_f32_e32 v116, v135, v135
	v_mul_f32_e32 v117, v133, v133
	v_fmac_f32_e32 v116, v134, v134
	v_fmac_f32_e32 v117, v132, v132
	v_add_f32_e32 v116, v116, v117
	v_add_f32_e32 v2, v2, v116
	v_mul_f32_e32 v116, v143, v143
	v_mul_f32_e32 v117, v141, v141
	v_fmac_f32_e32 v116, v142, v142
	v_fmac_f32_e32 v117, v140, v140
	v_add_f32_e32 v116, v116, v117
	v_add_f32_e32 v2, v2, v116
	v_mul_f32_e32 v116, v151, v151
	v_mul_f32_e32 v117, v149, v149
	v_fmac_f32_e32 v116, v150, v150
	v_fmac_f32_e32 v117, v148, v148
; __global__ void __launch_bounds__(512, 2) fwd_mega(Params P_by_kernarg) {
;     ...
;             P5_ROW(row, xa, ma, sA);
;             if (hasB) P5_ROW(rB, xb, mb, sB);
	v_add_f32_e32 v116, v116, v117
	v_add_f32_e32 v2, v2, v116
	v_mul_f32_e32 v116, v159, v159
	v_mul_f32_e32 v117, v157, v157
	v_fmac_f32_e32 v116, v158, v158
	v_fmac_f32_e32 v117, v156, v156
	v_add_f32_e32 v116, v116, v117
	v_add_f32_e32 v2, v2, v116
	v_mul_f32_e32 v116, v167, v167
	v_mul_f32_e32 v117, v165, v165
	v_fmac_f32_e32 v116, v166, v166
	v_fmac_f32_e32 v117, v164, v164
	v_add_f32_e32 v116, v116, v117
	v_add_f32_e32 v2, v2, v116
	v_mul_f32_e32 v116, v171, v171
	v_mul_f32_e32 v117, v169, v169
	v_fmac_f32_e32 v116, v170, v170
	v_fmac_f32_e32 v117, v168, v168
	v_add_f32_e32 v116, v116, v117
	v_add_f32_e32 v2, v2, v116
	v_mul_f32_e32 v116, v163, v163
	v_mul_f32_e32 v117, v161, v161
	v_fmac_f32_e32 v116, v162, v162
	v_fmac_f32_e32 v117, v160, v160
	v_add_f32_e32 v116, v116, v117
	v_add_f32_e32 v2, v2, v116
	v_mul_f32_e32 v116, v155, v155
	v_mul_f32_e32 v117, v153, v153
	v_fmac_f32_e32 v116, v154, v154
	v_fmac_f32_e32 v117, v152, v152
	v_add_f32_e32 v116, v116, v117
	v_add_f32_e32 v2, v2, v116
	v_mul_f32_e32 v116, v147, v147
	v_mul_f32_e32 v117, v145, v145
	v_fmac_f32_e32 v116, v146, v146
	v_fmac_f32_e32 v117, v144, v144
	v_add_f32_e32 v116, v116, v117
	v_add_f32_e32 v2, v2, v116
	v_mul_f32_e32 v116, v139, v139
	v_mul_f32_e32 v117, v137, v137
	v_fmac_f32_e32 v116, v138, v138
	v_pk_fma_f32 v[112:113], v[250:251], v[114:115], v[112:113]
	v_pk_fma_f32 v[114:115], v[248:249], v[108:109], v[186:187]
	v_fmac_f32_e32 v117, v136, v136
	v_cvt_pk_bf16_f32 v108, v114, v115
	v_cvt_pk_bf16_f32 v109, v112, v113
	global_store_dwordx2 v[106:107], v[108:109], off offset:3072
	s_nop 1
	v_add_f32_e32 v116, v116, v117
	v_add_f32_e32 v2, v2, v116
	v_mul_f32_e32 v116, v173, v173
	v_mul_f32_e32 v117, v185, v185
	v_fmac_f32_e32 v116, v172, v172
	v_fmac_f32_e32 v117, v184, v184
	v_add_f32_e32 v116, v116, v117
	v_add_f32_e32 v2, v2, v116
	v_mul_f32_e32 v116, v127, v127
	v_mul_f32_e32 v117, v129, v129
	v_fmac_f32_e32 v116, v126, v126
	v_fmac_f32_e32 v117, v128, v128
	v_mul_f32_e32 v115, v115, v115
	v_mul_f32_e32 v113, v113, v113
	v_add_f32_e32 v116, v116, v117
	v_fmac_f32_e32 v115, v114, v114
	v_fmac_f32_e32 v113, v112, v112
	v_add_f32_e32 v2, v2, v116
	v_add_f32_e32 v112, v115, v113
	v_add_f32_e32 v2, v2, v112
	v_pk_fma_f32 v[110:111], v[254:255], v[188:189], v[192:193]
	v_pk_fma_f32 v[112:113], v[252:253], v[182:183], v[190:191]
	v_mul_f32_e32 v109, v111, v111
	v_mul_f32_e32 v108, v113, v113
	v_fmac_f32_e32 v108, v112, v112
	v_fmac_f32_e32 v109, v110, v110
	v_add_f32_e32 v108, v108, v109
	v_add_f32_e32 v2, v2, v108
	ds_bpermute_b32 v108, v174, v2
	v_cvt_pk_bf16_f32 v112, v112, v113
	v_cvt_pk_bf16_f32 v113, v110, v111
	global_store_dwordx2 v[106:107], v[112:113], off offset:3584
	s_waitcnt lgkmcnt(0)
	v_add_f32_e32 v2, v2, v108
	ds_bpermute_b32 v108, v175, v2
	s_waitcnt lgkmcnt(0)
	v_add_f32_e32 v2, v2, v108
	ds_bpermute_b32 v108, v176, v2
	s_waitcnt lgkmcnt(0)
	v_add_f32_e32 v2, v2, v108
	ds_bpermute_b32 v108, v177, v2
	s_waitcnt lgkmcnt(0)
	v_add_f32_e32 v2, v2, v108
	ds_bpermute_b32 v108, v178, v2
	s_waitcnt lgkmcnt(0)
	v_add_f32_e32 v2, v2, v108
	ds_bpermute_b32 v108, v179, v2
	s_and_saveexec_b64 s[38:39], s[2:3]
	s_cbranch_execz .LBB0_804
	s_waitcnt lgkmcnt(0)
	v_add_f32_e32 v2, v2, v108
	v_fmamk_f32 v2, v2, 0x39800000, v180
	v_mul_f32_e32 v106, 0x4b800000, v2
	v_cmp_gt_f32_e32 vcc, s46, v2
	s_add_u32 s50, s6, s41
	s_addc_u32 s51, s7, s42
	v_cndmask_b32_e32 v2, v2, v106, vcc
	v_rsq_f32_e32 v2, v2
	s_nop 0
	v_mul_f32_e32 v106, 0x45800000, v2
	v_cndmask_b32_e32 v2, v2, v106, vcc
	global_store_dword v3, v2, s[50:51]
.LBB0_804:
	s_or_b64 exec, exec, s[38:39]
	s_andn2_b64 vcc, exec, s[36:37]
	s_cbranch_vccnz .LBB0_801
	s_waitcnt lgkmcnt(0)
	global_load_dwordx4 v[108:111], v[10:11], off
	ds_bpermute_b32 v2, v174, v181
	v_lshlrev_b32_e32 v114, 16, v102
	v_and_b32_e32 v115, 0xffff0000, v102
	s_lshl_b64 s[36:37], s[34:35], 12
	v_lshlrev_b32_e32 v112, 16, v104
	s_waitcnt lgkmcnt(0)
	v_add_f32_e32 v2, v181, v2
	ds_bpermute_b32 v106, v175, v2
	v_and_b32_e32 v113, 0xffff0000, v104
	v_lshlrev_b32_e32 v104, 16, v105
	v_and_b32_e32 v105, 0xffff0000, v105
	v_and_b32_e32 v117, 0xffff0000, v71
	s_waitcnt lgkmcnt(0)
	v_add_f32_e32 v2, v2, v106
	ds_bpermute_b32 v106, v176, v2
	v_lshlrev_b32_e32 v118, 16, v42
	v_and_b32_e32 v119, 0xffff0000, v42
	v_lshlrev_b32_e32 v120, 16, v43
	v_and_b32_e32 v121, 0xffff0000, v43
	s_waitcnt lgkmcnt(0)
	v_add_f32_e32 v2, v2, v106
	ds_bpermute_b32 v106, v177, v2
	s_waitcnt lgkmcnt(0)
	v_add_f32_e32 v2, v2, v106
	ds_bpermute_b32 v106, v178, v2
	s_waitcnt lgkmcnt(0)
	v_add_f32_e32 v2, v2, v106
	ds_bpermute_b32 v106, v179, v2
	s_waitcnt lgkmcnt(0)
	v_add_f32_e32 v2, v2, v106
	v_fmamk_f32 v2, v2, 0x39800000, v180
	v_mul_f32_e32 v102, 0x4b800000, v2
	v_cmp_gt_f32_e32 vcc, s46, v2
	v_lshl_add_u64 v[106:107], s[36:37], 1, v[12:13]
	s_nop 0
	v_cndmask_b32_e32 v2, v2, v102, vcc
	v_rsq_f32_e32 v2, v2
	v_lshlrev_b32_e32 v102, 16, v103
	v_and_b32_e32 v103, 0xffff0000, v103
	v_mul_f32_e32 v116, 0x45800000, v2
	v_cndmask_b32_e32 v2, v2, v116, vcc
	v_pk_mul_f32 v[112:113], v[2:3], v[112:113] op_sel_hi:[0,1]
	v_pk_mul_f32 v[104:105], v[2:3], v[104:105] op_sel_hi:[0,1]
	v_lshlrev_b32_e32 v116, 16, v71
	s_waitcnt vmcnt(0)
; __global__ void __launch_bounds__(512, 2) fwd_mega(Params P_by_kernarg) {
;     ...
;             P5_ROW(row, xa, ma, sA);
;             if (hasB) P5_ROW(rB, xb, mb, sB);
	v_pk_fma_f32 v[102:103], v[110:111], v[104:105], v[102:103]
	v_pk_fma_f32 v[104:105], v[108:109], v[112:113], v[114:115]
	v_lshlrev_b32_e32 v112, 16, v100
	v_cvt_pk_bf16_f32 v108, v104, v105
	v_cvt_pk_bf16_f32 v109, v102, v103
	global_store_dwordx2 v[106:107], v[108:109], off
	s_nop 1
	v_and_b32_e32 v113, 0xffff0000, v100
	v_lshlrev_b32_e32 v100, 16, v101
	v_and_b32_e32 v101, 0xffff0000, v101
	v_lshlrev_b32_e32 v114, 16, v98
	v_and_b32_e32 v115, 0xffff0000, v98
	v_lshlrev_b32_e32 v98, 16, v99
	v_and_b32_e32 v99, 0xffff0000, v99
	v_pk_mul_f32 v[112:113], v[2:3], v[112:113] op_sel_hi:[0,1]
	v_pk_mul_f32 v[100:101], v[2:3], v[100:101] op_sel_hi:[0,1]
	v_pk_fma_f32 v[98:99], v[198:199], v[100:101], v[98:99]
	v_pk_fma_f32 v[100:101], v[194:195], v[112:113], v[114:115]
	v_lshlrev_b32_e32 v112, 16, v96
	v_cvt_pk_bf16_f32 v108, v100, v101
	v_cvt_pk_bf16_f32 v109, v98, v99
	global_store_dwordx2 v[106:107], v[108:109], off offset:512
	s_nop 1
	v_and_b32_e32 v113, 0xffff0000, v96
	v_lshlrev_b32_e32 v96, 16, v97
	v_and_b32_e32 v97, 0xffff0000, v97
	v_lshlrev_b32_e32 v114, 16, v94
	v_and_b32_e32 v115, 0xffff0000, v94
	v_lshlrev_b32_e32 v94, 16, v95
	v_and_b32_e32 v95, 0xffff0000, v95
	v_pk_mul_f32 v[112:113], v[2:3], v[112:113] op_sel_hi:[0,1]
	v_pk_mul_f32 v[96:97], v[2:3], v[96:97] op_sel_hi:[0,1]
	v_pk_fma_f32 v[94:95], v[202:203], v[96:97], v[94:95]
	v_pk_fma_f32 v[96:97], v[200:201], v[112:113], v[114:115]
	v_lshlrev_b32_e32 v112, 16, v92
	v_cvt_pk_bf16_f32 v108, v96, v97
	v_cvt_pk_bf16_f32 v109, v94, v95
	global_store_dwordx2 v[106:107], v[108:109], off offset:1024
	s_nop 1
	v_and_b32_e32 v113, 0xffff0000, v92
	v_lshlrev_b32_e32 v92, 16, v93
	v_and_b32_e32 v93, 0xffff0000, v93
	v_lshlrev_b32_e32 v114, 16, v90
	v_and_b32_e32 v115, 0xffff0000, v90
	v_lshlrev_b32_e32 v90, 16, v91
	v_and_b32_e32 v91, 0xffff0000, v91
	v_pk_mul_f32 v[112:113], v[2:3], v[112:113] op_sel_hi:[0,1]
	v_pk_mul_f32 v[92:93], v[2:3], v[92:93] op_sel_hi:[0,1]
	v_pk_fma_f32 v[90:91], v[206:207], v[92:93], v[90:91]
	v_pk_fma_f32 v[92:93], v[204:205], v[112:113], v[114:115]
	v_lshlrev_b32_e32 v112, 16, v88
	v_cvt_pk_bf16_f32 v108, v92, v93
	v_cvt_pk_bf16_f32 v109, v90, v91
	global_store_dwordx2 v[106:107], v[108:109], off offset:1536
	s_nop 1
	v_and_b32_e32 v113, 0xffff0000, v88
	v_lshlrev_b32_e32 v88, 16, v89
	v_and_b32_e32 v89, 0xffff0000, v89
	v_lshlrev_b32_e32 v114, 16, v86
	v_and_b32_e32 v115, 0xffff0000, v86
	v_lshlrev_b32_e32 v86, 16, v87
	v_and_b32_e32 v87, 0xffff0000, v87
	v_pk_mul_f32 v[112:113], v[2:3], v[112:113] op_sel_hi:[0,1]
	v_pk_mul_f32 v[88:89], v[2:3], v[88:89] op_sel_hi:[0,1]
	v_pk_fma_f32 v[86:87], v[210:211], v[88:89], v[86:87]
	v_pk_fma_f32 v[88:89], v[208:209], v[112:113], v[114:115]
	v_lshlrev_b32_e32 v112, 16, v84
	v_cvt_pk_bf16_f32 v108, v88, v89
	v_cvt_pk_bf16_f32 v109, v86, v87
	global_store_dwordx2 v[106:107], v[108:109], off offset:2048
	s_nop 1
	v_and_b32_e32 v113, 0xffff0000, v84
	v_lshlrev_b32_e32 v84, 16, v85
	v_and_b32_e32 v85, 0xffff0000, v85
	v_lshlrev_b32_e32 v114, 16, v82
	v_and_b32_e32 v115, 0xffff0000, v82
	v_lshlrev_b32_e32 v82, 16, v83
	v_and_b32_e32 v83, 0xffff0000, v83
	v_pk_mul_f32 v[112:113], v[2:3], v[112:113] op_sel_hi:[0,1]
	v_pk_mul_f32 v[84:85], v[2:3], v[84:85] op_sel_hi:[0,1]
	v_pk_fma_f32 v[82:83], v[214:215], v[84:85], v[82:83]
	v_pk_fma_f32 v[84:85], v[212:213], v[112:113], v[114:115]
	v_lshlrev_b32_e32 v112, 16, v80
	v_cvt_pk_bf16_f32 v108, v84, v85
	v_cvt_pk_bf16_f32 v109, v82, v83
	global_store_dwordx2 v[106:107], v[108:109], off offset:2560
	s_nop 1
	v_and_b32_e32 v113, 0xffff0000, v80
	v_lshlrev_b32_e32 v80, 16, v81
	v_and_b32_e32 v81, 0xffff0000, v81
	v_lshlrev_b32_e32 v114, 16, v78
	v_and_b32_e32 v115, 0xffff0000, v78
	v_lshlrev_b32_e32 v78, 16, v79
	v_and_b32_e32 v79, 0xffff0000, v79
	v_pk_mul_f32 v[112:113], v[2:3], v[112:113] op_sel_hi:[0,1]
	v_pk_mul_f32 v[80:81], v[2:3], v[80:81] op_sel_hi:[0,1]
	v_pk_fma_f32 v[78:79], v[218:219], v[80:81], v[78:79]
	v_pk_fma_f32 v[80:81], v[216:217], v[112:113], v[114:115]
	v_lshlrev_b32_e32 v112, 16, v76
	v_cvt_pk_bf16_f32 v108, v80, v81
	v_cvt_pk_bf16_f32 v109, v78, v79
	global_store_dwordx2 v[106:107], v[108:109], off offset:3072
	s_nop 1
	v_and_b32_e32 v113, 0xffff0000, v76
	v_lshlrev_b32_e32 v76, 16, v77
	v_and_b32_e32 v77, 0xffff0000, v77
	v_lshlrev_b32_e32 v114, 16, v74
	v_and_b32_e32 v115, 0xffff0000, v74
	v_lshlrev_b32_e32 v74, 16, v75
	v_and_b32_e32 v75, 0xffff0000, v75
	v_pk_mul_f32 v[112:113], v[2:3], v[112:113] op_sel_hi:[0,1]
	v_pk_mul_f32 v[76:77], v[2:3], v[76:77] op_sel_hi:[0,1]
	v_pk_fma_f32 v[74:75], v[222:223], v[76:77], v[74:75]
	v_pk_fma_f32 v[76:77], v[220:221], v[112:113], v[114:115]
	v_lshlrev_b32_e32 v112, 16, v72
	v_cvt_pk_bf16_f32 v108, v76, v77
	v_cvt_pk_bf16_f32 v109, v74, v75
	global_store_dwordx2 v[106:107], v[108:109], off offset:3584
	s_nop 1
	v_and_b32_e32 v113, 0xffff0000, v72
	v_lshlrev_b32_e32 v72, 16, v73
	v_and_b32_e32 v73, 0xffff0000, v73
	v_lshlrev_b32_e32 v114, 16, v70
	v_and_b32_e32 v115, 0xffff0000, v70
	v_add_co_u32_e32 v70, vcc, s45, v106
	v_pk_mul_f32 v[72:73], v[2:3], v[72:73] op_sel_hi:[0,1]
	s_nop 0
	v_addc_co_u32_e32 v71, vcc, 0, v107, vcc
	v_pk_mul_f32 v[106:107], v[2:3], v[112:113] op_sel_hi:[0,1]
	v_lshlrev_b32_e32 v112, 16, v68
	v_and_b32_e32 v113, 0xffff0000, v68
	v_lshlrev_b32_e32 v68, 16, v69
	v_and_b32_e32 v69, 0xffff0000, v69
	v_pk_mul_f32 v[112:113], v[2:3], v[112:113] op_sel_hi:[0,1]
	v_pk_mul_f32 v[68:69], v[2:3], v[68:69] op_sel_hi:[0,1]
	v_pk_fma_f32 v[72:73], v[226:227], v[72:73], v[116:117]
	v_pk_fma_f32 v[106:107], v[224:225], v[106:107], v[114:115]
	v_lshlrev_b32_e32 v114, 16, v66
	v_cvt_pk_bf16_f32 v108, v106, v107
	v_cvt_pk_bf16_f32 v109, v72, v73
	global_store_dwordx2 v[70:71], v[108:109], off
	s_nop 1
	v_and_b32_e32 v115, 0xffff0000, v66
	v_lshlrev_b32_e32 v66, 16, v67
	v_and_b32_e32 v67, 0xffff0000, v67
	v_lshlrev_b32_e32 v116, 16, v44
	v_and_b32_e32 v117, 0xffff0000, v44
	v_lshlrev_b32_e32 v44, 16, v45
	v_and_b32_e32 v45, 0xffff0000, v45
	v_pk_fma_f32 v[66:67], v[230:231], v[68:69], v[66:67]
	v_pk_fma_f32 v[68:69], v[228:229], v[112:113], v[114:115]
	v_lshlrev_b32_e32 v112, 16, v64
	v_cvt_pk_bf16_f32 v108, v68, v69
	v_cvt_pk_bf16_f32 v109, v66, v67
	global_store_dwordx2 v[70:71], v[108:109], off offset:512
	s_nop 1
	v_and_b32_e32 v113, 0xffff0000, v64
	v_lshlrev_b32_e32 v64, 16, v65
	v_and_b32_e32 v65, 0xffff0000, v65
	v_lshlrev_b32_e32 v114, 16, v62
	v_and_b32_e32 v115, 0xffff0000, v62
	v_lshlrev_b32_e32 v62, 16, v63
	v_and_b32_e32 v63, 0xffff0000, v63
	v_pk_mul_f32 v[112:113], v[2:3], v[112:113] op_sel_hi:[0,1]
	v_pk_mul_f32 v[64:65], v[2:3], v[64:65] op_sel_hi:[0,1]
	v_pk_fma_f32 v[62:63], v[234:235], v[64:65], v[62:63]
	v_pk_fma_f32 v[64:65], v[232:233], v[112:113], v[114:115]
	v_lshlrev_b32_e32 v112, 16, v60
	v_cvt_pk_bf16_f32 v108, v64, v65
	v_cvt_pk_bf16_f32 v109, v62, v63
	global_store_dwordx2 v[70:71], v[108:109], off offset:1024
	s_nop 1
	v_and_b32_e32 v113, 0xffff0000, v60
	v_lshlrev_b32_e32 v60, 16, v61
	v_and_b32_e32 v61, 0xffff0000, v61
	v_lshlrev_b32_e32 v114, 16, v58
	v_and_b32_e32 v115, 0xffff0000, v58
	v_lshlrev_b32_e32 v58, 16, v59
	v_and_b32_e32 v59, 0xffff0000, v59
	v_pk_mul_f32 v[112:113], v[2:3], v[112:113] op_sel_hi:[0,1]
	v_pk_mul_f32 v[60:61], v[2:3], v[60:61] op_sel_hi:[0,1]
	v_pk_fma_f32 v[58:59], v[238:239], v[60:61], v[58:59]
	v_pk_fma_f32 v[60:61], v[236:237], v[112:113], v[114:115]
	v_lshlrev_b32_e32 v112, 16, v56
	v_cvt_pk_bf16_f32 v108, v60, v61
	v_cvt_pk_bf16_f32 v109, v58, v59
	global_store_dwordx2 v[70:71], v[108:109], off offset:1536
	s_nop 1
	v_and_b32_e32 v113, 0xffff0000, v56
	v_lshlrev_b32_e32 v56, 16, v57
	v_and_b32_e32 v57, 0xffff0000, v57
	v_lshlrev_b32_e32 v114, 16, v54
	v_and_b32_e32 v115, 0xffff0000, v54
	v_lshlrev_b32_e32 v54, 16, v55
	v_and_b32_e32 v55, 0xffff0000, v55
	v_pk_mul_f32 v[112:113], v[2:3], v[112:113] op_sel_hi:[0,1]
	v_pk_mul_f32 v[56:57], v[2:3], v[56:57] op_sel_hi:[0,1]
	v_pk_fma_f32 v[110:111], v[242:243], v[56:57], v[54:55]
	v_pk_fma_f32 v[108:109], v[240:241], v[112:113], v[114:115]
	v_lshlrev_b32_e32 v112, 16, v52
	v_cvt_pk_bf16_f32 v54, v108, v109
	v_cvt_pk_bf16_f32 v55, v110, v111
	global_store_dwordx2 v[70:71], v[54:55], off offset:2048
	s_nop 1
	v_and_b32_e32 v113, 0xffff0000, v52
	v_lshlrev_b32_e32 v52, 16, v53
	v_and_b32_e32 v53, 0xffff0000, v53
	v_lshlrev_b32_e32 v114, 16, v50
	v_and_b32_e32 v115, 0xffff0000, v50
	v_lshlrev_b32_e32 v50, 16, v51
	v_and_b32_e32 v51, 0xffff0000, v51
	v_pk_mul_f32 v[112:113], v[2:3], v[112:113] op_sel_hi:[0,1]
	v_pk_mul_f32 v[52:53], v[2:3], v[52:53] op_sel_hi:[0,1]
	v_pk_fma_f32 v[56:57], v[246:247], v[52:53], v[50:51]
	v_pk_fma_f32 v[54:55], v[244:245], v[112:113], v[114:115]
	v_lshlrev_b32_e32 v112, 16, v48
	v_cvt_pk_bf16_f32 v50, v54, v55
	v_cvt_pk_bf16_f32 v51, v56, v57
	global_store_dwordx2 v[70:71], v[50:51], off offset:2560
	s_nop 1
	v_and_b32_e32 v113, 0xffff0000, v48
	v_lshlrev_b32_e32 v48, 16, v49
	v_and_b32_e32 v49, 0xffff0000, v49
	v_pk_mul_f32 v[42:43], v[2:3], v[112:113] op_sel_hi:[0,1]
	v_pk_mul_f32 v[48:49], v[2:3], v[48:49] op_sel_hi:[0,1]
	v_pk_mul_f32 v[112:113], v[2:3], v[116:117] op_sel_hi:[0,1]
	v_pk_mul_f32 v[116:117], v[2:3], v[44:45] op_sel_hi:[0,1]
	v_mul_f32_e32 v2, v105, v105
	v_mul_f32_e32 v44, v103, v103
	v_fmac_f32_e32 v2, v104, v104
	v_fmac_f32_e32 v44, v102, v102
	v_lshlrev_b32_e32 v114, 16, v46
	v_and_b32_e32 v115, 0xffff0000, v46
	v_lshlrev_b32_e32 v46, 16, v47
	v_and_b32_e32 v47, 0xffff0000, v47
	v_add_f32_e32 v2, v2, v44
	v_mul_f32_e32 v44, v101, v101
	v_mul_f32_e32 v45, v99, v99
	v_fmac_f32_e32 v44, v100, v100
	v_fmac_f32_e32 v45, v98, v98
	v_add_f32_e32 v98, v44, v45
	v_add_f32_e32 v2, v2, v98
	v_pk_fma_f32 v[46:47], v[250:251], v[48:49], v[46:47]
	v_pk_fma_f32 v[48:49], v[248:249], v[42:43], v[114:115]
	v_mul_f32_e32 v50, v97, v97
	v_cvt_pk_bf16_f32 v42, v48, v49
	v_cvt_pk_bf16_f32 v43, v46, v47
	global_store_dwordx2 v[70:71], v[42:43], off offset:3072
	s_nop 1
	v_mul_f32_e32 v51, v95, v95
	v_fmac_f32_e32 v50, v96, v96
	v_fmac_f32_e32 v51, v94, v94
	v_add_f32_e32 v50, v50, v51
	v_add_f32_e32 v2, v2, v50
	v_mul_f32_e32 v50, v93, v93
	v_mul_f32_e32 v51, v91, v91
	v_fmac_f32_e32 v50, v92, v92
	v_fmac_f32_e32 v51, v90, v90
	v_add_f32_e32 v50, v50, v51
	v_add_f32_e32 v2, v2, v50
	v_mul_f32_e32 v50, v89, v89
	v_mul_f32_e32 v51, v87, v87
	v_fmac_f32_e32 v50, v88, v88
	v_fmac_f32_e32 v51, v86, v86
	v_add_f32_e32 v50, v50, v51
	v_add_f32_e32 v2, v2, v50
	v_mul_f32_e32 v50, v85, v85
	v_mul_f32_e32 v51, v83, v83
	v_fmac_f32_e32 v50, v84, v84
	v_fmac_f32_e32 v51, v82, v82
	v_add_f32_e32 v50, v50, v51
	v_add_f32_e32 v2, v2, v50
	v_mul_f32_e32 v50, v81, v81
	v_mul_f32_e32 v51, v79, v79
	v_fmac_f32_e32 v50, v80, v80
	v_fmac_f32_e32 v51, v78, v78
	v_add_f32_e32 v50, v50, v51
	v_add_f32_e32 v2, v2, v50
	v_mul_f32_e32 v50, v77, v77
	v_mul_f32_e32 v51, v75, v75
	v_fmac_f32_e32 v50, v76, v76
	v_fmac_f32_e32 v51, v74, v74
	v_add_f32_e32 v50, v50, v51
	v_add_f32_e32 v2, v2, v50
	v_mul_f32_e32 v50, v107, v107
	v_mul_f32_e32 v51, v73, v73
	v_fmac_f32_e32 v50, v106, v106
	v_fmac_f32_e32 v51, v72, v72
	v_add_f32_e32 v50, v50, v51
	v_add_f32_e32 v2, v2, v50
	v_mul_f32_e32 v50, v69, v69
	v_mul_f32_e32 v51, v67, v67
	v_fmac_f32_e32 v50, v68, v68
	v_fmac_f32_e32 v51, v66, v66
	v_add_f32_e32 v50, v50, v51
	v_add_f32_e32 v2, v2, v50
	v_mul_f32_e32 v50, v65, v65
	v_mul_f32_e32 v51, v63, v63
	v_fmac_f32_e32 v50, v64, v64
	v_fmac_f32_e32 v51, v62, v62
	v_add_f32_e32 v50, v50, v51
	v_add_f32_e32 v2, v2, v50
	v_mul_f32_e32 v50, v61, v61
	v_mul_f32_e32 v51, v59, v59
	v_fmac_f32_e32 v50, v60, v60
	v_fmac_f32_e32 v51, v58, v58
	v_add_f32_e32 v50, v50, v51
	v_add_f32_e32 v2, v2, v50
	v_mul_f32_e32 v50, v109, v109
	v_mul_f32_e32 v51, v111, v111
	v_fmac_f32_e32 v50, v108, v108
	v_fmac_f32_e32 v51, v110, v110
	v_add_f32_e32 v50, v50, v51
	v_add_f32_e32 v2, v2, v50
	v_mul_f32_e32 v50, v55, v55
	v_mul_f32_e32 v51, v57, v57
	v_fmac_f32_e32 v50, v54, v54
	v_fmac_f32_e32 v51, v56, v56
	v_mul_f32_e32 v49, v49, v49
	v_mul_f32_e32 v47, v47, v47
	v_add_f32_e32 v50, v50, v51
	v_fmac_f32_e32 v49, v48, v48
	v_fmac_f32_e32 v47, v46, v46
	v_add_f32_e32 v2, v2, v50
	v_add_f32_e32 v46, v49, v47
	v_add_f32_e32 v2, v2, v46
	v_pk_fma_f32 v[44:45], v[254:255], v[116:117], v[120:121]
	v_pk_fma_f32 v[46:47], v[252:253], v[112:113], v[118:119]
	v_mul_f32_e32 v43, v45, v45
	v_mul_f32_e32 v42, v47, v47
	v_fmac_f32_e32 v42, v46, v46
	v_fmac_f32_e32 v43, v44, v44
	v_add_f32_e32 v42, v42, v43
	v_add_f32_e32 v2, v2, v42
	ds_bpermute_b32 v42, v174, v2
	v_cvt_pk_bf16_f32 v46, v46, v47
	v_cvt_pk_bf16_f32 v47, v44, v45
	global_store_dwordx2 v[70:71], v[46:47], off offset:3584
	s_waitcnt lgkmcnt(0)
; __device__ __forceinline__ float wave_sum(float v) {
; #pragma unroll
;     for (int o = 1; o < 64; o <<= 1) v += __shfl_xor(v, o);
;     return v;
	v_add_f32_e32 v2, v2, v42
	ds_bpermute_b32 v42, v175, v2
	s_waitcnt lgkmcnt(0)
	v_add_f32_e32 v2, v2, v42
	ds_bpermute_b32 v42, v176, v2
	s_waitcnt lgkmcnt(0)
	v_add_f32_e32 v2, v2, v42
	ds_bpermute_b32 v42, v177, v2
	s_waitcnt lgkmcnt(0)
	v_add_f32_e32 v2, v2, v42
	ds_bpermute_b32 v42, v178, v2
	s_waitcnt lgkmcnt(0)
	v_add_f32_e32 v2, v2, v42
	ds_bpermute_b32 v42, v179, v2
	s_and_saveexec_b64 s[36:37], s[2:3]
	s_cbranch_execz .LBB0_800
	s_waitcnt lgkmcnt(0)
	v_add_f32_e32 v2, v2, v42
	v_fmamk_f32 v2, v2, 0x39800000, v180
	v_mul_f32_e32 v42, 0x4b800000, v2
	v_cmp_gt_f32_e32 vcc, s46, v2
	s_lshl_b64 s[34:35], s[34:35], 2
	s_add_u32 s34, s21, s34
	v_cndmask_b32_e32 v2, v2, v42, vcc
	v_rsq_f32_e32 v2, v2
	s_addc_u32 s35, s40, s35
	v_mul_f32_e32 v42, 0x45800000, v2
	v_cndmask_b32_e32 v2, v2, v42, vcc
	global_store_dword v3, v2, s[34:35]
	s_branch .LBB0_800
